# GEMM MMA segments: the back-to-back lower/raise priority pair between the two 16-MFMA clusters removed (priority stays raised across both)
# baseline (speedup 1.0000x reference)
.LBB0_68:
	s_add_u32 s21, s54, s56
	s_addc_u32 s36, s55, s57
	s_add_u32 s21, s21, 0x100
	s_addc_u32 s64, s36, 0
	s_add_u32 s94, s96, s56
	s_addc_u32 s65, s97, s57
	s_add_i32 s95, 0, 0x10000
	s_cmpk_eq_i32 s56, 0x700
	s_cselect_b64 s[68:69], -1, 0
	s_and_b64 s[36:37], s[68:69], exec
	s_cselect_b32 s67, s43, s64
	s_cselect_b32 s66, s90, s21
	v_add_u32_e32 v80, s95, v239
	s_cselect_b32 s65, s41, s65
	s_cselect_b32 s64, s72, s94
	s_add_i32 s21, 0, 0x14000
	ds_read_b128 v[154:157], v80
	ds_read_b128 v[158:161], v80 offset:1024
	ds_read_b128 v[162:165], v80 offset:2048
	ds_read_b128 v[166:169], v80 offset:3072
	v_add_u32_e32 v80, s21, v239
	ds_read_b128 v[130:133], v80
	ds_read_b128 v[142:145], v80 offset:1024
	ds_read_b128 v[146:149], v80 offset:2048
	ds_read_b128 v[150:153], v80 offset:3072
	s_waitcnt lgkmcnt(0)
	v_lshl_add_u64 v[114:115], v[218:219], 0, s[56:57]
	s_add_i32 m0, s51, 0xc000
	ds_read_b128 v[170:173], v241
	ds_read_b128 v[174:177], v241 offset:1024
	ds_read_b128 v[178:181], v241 offset:2048
	ds_read_b128 v[182:185], v241 offset:3072
	ds_read_b128 v[186:189], v241 offset:4096
	ds_read_b128 v[190:193], v241 offset:5120
	ds_read_b128 v[198:201], v241 offset:6144
	ds_read_b128 v[220:223], v241 offset:7168
	global_load_lds_dwordx4 v[114:115], off
	v_lshl_add_u64 v[114:115], v[216:217], 0, s[56:57]
	s_add_i32 m0, s51, 0xe000
	s_nop 0
	global_load_lds_dwordx4 v[114:115], off
	s_waitcnt vmcnt(8)
	s_waitcnt lgkmcnt(0)
	s_barrier
	s_setprio 1
	s_waitcnt lgkmcnt(0)
	v_mfma_f32_16x16x32_bf16 v[114:117], v[154:157], v[170:173], v[138:141]
	v_mfma_f32_16x16x32_bf16 v[126:129], v[162:165], v[170:173], v[134:137]
	v_mfma_f32_16x16x32_bf16 v[122:125], v[154:157], v[178:181], v[122:125]
	v_mfma_f32_16x16x32_bf16 v[118:121], v[162:165], v[178:181], v[118:121]
	v_mfma_f32_16x16x32_bf16 v[110:113], v[154:157], v[186:189], v[110:113]
	v_mfma_f32_16x16x32_bf16 v[106:109], v[162:165], v[186:189], v[106:109]
	v_mfma_f32_16x16x32_bf16 v[102:105], v[154:157], v[198:201], v[102:105]
	v_mfma_f32_16x16x32_bf16 v[98:101], v[162:165], v[198:201], v[98:101]
	v_mfma_f32_16x16x32_bf16 v[114:117], v[158:161], v[174:177], v[114:117]
	v_mfma_f32_16x16x32_bf16 v[126:129], v[166:169], v[174:177], v[126:129]
	v_mfma_f32_16x16x32_bf16 v[122:125], v[158:161], v[182:185], v[122:125]
	v_mfma_f32_16x16x32_bf16 v[118:121], v[166:169], v[182:185], v[118:121]
	v_mfma_f32_16x16x32_bf16 v[110:113], v[158:161], v[190:193], v[110:113]
	v_mfma_f32_16x16x32_bf16 v[106:109], v[166:169], v[190:193], v[106:109]
	v_mfma_f32_16x16x32_bf16 v[102:105], v[158:161], v[220:223], v[102:105]
	v_mfma_f32_16x16x32_bf16 v[98:101], v[166:169], v[220:223], v[98:101]
	v_mfma_f32_16x16x32_bf16 v[86:89], v[130:133], v[170:173], v[86:89]
	v_mfma_f32_16x16x32_bf16 v[82:85], v[146:149], v[170:173], v[82:85]
	v_mfma_f32_16x16x32_bf16 v[68:71], v[130:133], v[178:181], v[68:71]
	v_mfma_f32_16x16x32_bf16 v[64:67], v[146:149], v[178:181], v[64:67]
	v_mfma_f32_16x16x32_bf16 v[52:55], v[130:133], v[186:189], v[52:55]
	v_mfma_f32_16x16x32_bf16 v[48:51], v[146:149], v[186:189], v[48:51]
	v_mfma_f32_16x16x32_bf16 v[36:39], v[130:133], v[198:201], v[36:39]
	v_mfma_f32_16x16x32_bf16 v[32:35], v[146:149], v[198:201], v[32:35]
	v_mfma_f32_16x16x32_bf16 v[86:89], v[142:145], v[174:177], v[86:89]
	v_mfma_f32_16x16x32_bf16 v[82:85], v[150:153], v[174:177], v[82:85]
	v_mfma_f32_16x16x32_bf16 v[68:71], v[142:145], v[182:185], v[68:71]
	v_mfma_f32_16x16x32_bf16 v[64:67], v[150:153], v[182:185], v[64:67]
	v_mfma_f32_16x16x32_bf16 v[52:55], v[142:145], v[190:193], v[52:55]
	v_mfma_f32_16x16x32_bf16 v[48:51], v[150:153], v[190:193], v[48:51]
	v_mfma_f32_16x16x32_bf16 v[36:39], v[142:145], v[220:223], v[36:39]
	v_mfma_f32_16x16x32_bf16 v[32:35], v[150:153], v[220:223], v[32:35]
	s_setprio 0
	s_barrier
	s_add_i32 s36, s95, s79
	v_lshl_add_u64 v[220:221], s[64:65], 0, v[206:207]
	s_mov_b32 m0, s36
	ds_read_b128 v[186:189], v241 offset:16384
	ds_read_b128 v[190:193], v241 offset:17408
	ds_read_b128 v[178:181], v241 offset:18432
	ds_read_b128 v[182:185], v241 offset:19456
	ds_read_b128 v[170:173], v241 offset:20480
	ds_read_b128 v[174:177], v241 offset:21504
	ds_read_b128 v[134:137], v241 offset:22528
	ds_read_b128 v[138:141], v241 offset:23552
	global_load_lds_dwordx4 v[220:221], off
	s_add_i32 m0, s36, 0x2000
	s_add_u32 s36, s64, 0x40000
	v_lshl_add_u64 v[222:223], s[64:65], 0, v[210:211]
	s_addc_u32 s37, s65, 0
	s_add_i32 s21, s21, s79
	global_load_lds_dwordx4 v[222:223], off
	v_lshl_add_u64 v[198:199], s[36:37], 0, v[206:207]
	s_mov_b32 m0, s21
	v_lshl_add_u64 v[224:225], s[66:67], 0, v[194:195]
	global_load_lds_dwordx4 v[198:199], off
	v_lshl_add_u64 v[198:199], s[36:37], 0, v[210:211]
	s_add_i32 m0, s21, 0x2000
	v_lshl_add_u64 v[226:227], s[66:67], 0, v[208:209]
	global_load_lds_dwordx4 v[198:199], off
	s_mov_b32 m0, s51
	v_cndmask_b32_e64 v80, 0, 1, s[62:63]
	global_load_lds_dwordx4 v[224:225], off
	s_mov_b32 m0, s53
	v_cmp_ne_u32_e64 s[36:37], 1, v80
	global_load_lds_dwordx4 v[226:227], off
	s_waitcnt vmcnt(8)
	s_waitcnt lgkmcnt(0)
	s_andn2_b64 vcc, exec, s[62:63]
	s_barrier
	s_cbranch_vccnz .LBB0_70
	s_setprio 1
	s_waitcnt lgkmcnt(0)
	v_mfma_f32_16x16x32_bf16 v[94:97], v[154:157], v[186:189], v[94:97]
	v_mfma_f32_16x16x32_bf16 v[90:93], v[162:165], v[186:189], v[90:93]
	v_mfma_f32_16x16x32_bf16 v[76:79], v[154:157], v[178:181], v[76:79]
	v_mfma_f32_16x16x32_bf16 v[72:75], v[162:165], v[178:181], v[72:75]
	v_mfma_f32_16x16x32_bf16 v[60:63], v[154:157], v[170:173], v[60:63]
	v_mfma_f32_16x16x32_bf16 v[56:59], v[162:165], v[170:173], v[56:59]
	v_mfma_f32_16x16x32_bf16 v[44:47], v[154:157], v[134:137], v[44:47]
	v_mfma_f32_16x16x32_bf16 v[40:43], v[162:165], v[134:137], v[40:43]
	v_mfma_f32_16x16x32_bf16 v[94:97], v[158:161], v[190:193], v[94:97]
	v_mfma_f32_16x16x32_bf16 v[90:93], v[166:169], v[190:193], v[90:93]
	v_mfma_f32_16x16x32_bf16 v[76:79], v[158:161], v[182:185], v[76:79]
	v_mfma_f32_16x16x32_bf16 v[72:75], v[166:169], v[182:185], v[72:75]
	v_mfma_f32_16x16x32_bf16 v[60:63], v[158:161], v[174:177], v[60:63]
	v_mfma_f32_16x16x32_bf16 v[56:59], v[166:169], v[174:177], v[56:59]
	v_mfma_f32_16x16x32_bf16 v[44:47], v[158:161], v[138:141], v[44:47]
	v_mfma_f32_16x16x32_bf16 v[40:43], v[166:169], v[138:141], v[40:43]
	v_mfma_f32_16x16x32_bf16 v[28:31], v[130:133], v[186:189], v[28:31]
	v_mfma_f32_16x16x32_bf16 v[24:27], v[146:149], v[186:189], v[24:27]
	v_mfma_f32_16x16x32_bf16 v[20:23], v[130:133], v[178:181], v[20:23]
	v_mfma_f32_16x16x32_bf16 v[16:19], v[146:149], v[178:181], v[16:19]
	v_mfma_f32_16x16x32_bf16 v[12:15], v[130:133], v[170:173], v[12:15]
	v_mfma_f32_16x16x32_bf16 v[8:11], v[146:149], v[170:173], v[8:11]
	v_mfma_f32_16x16x32_bf16 v[4:7], v[130:133], v[134:137], v[4:7]
	v_mfma_f32_16x16x32_bf16 v[0:3], v[146:149], v[134:137], v[0:3]
	v_mfma_f32_16x16x32_bf16 v[28:31], v[142:145], v[190:193], v[28:31]
	v_mfma_f32_16x16x32_bf16 v[24:27], v[150:153], v[190:193], v[24:27]
	v_mfma_f32_16x16x32_bf16 v[20:23], v[142:145], v[182:185], v[20:23]
	v_mfma_f32_16x16x32_bf16 v[16:19], v[150:153], v[182:185], v[16:19]
	v_mfma_f32_16x16x32_bf16 v[12:15], v[142:145], v[174:177], v[12:15]
	v_mfma_f32_16x16x32_bf16 v[8:11], v[150:153], v[174:177], v[8:11]
	v_mfma_f32_16x16x32_bf16 v[4:7], v[142:145], v[138:141], v[4:7]
	v_mfma_f32_16x16x32_bf16 v[0:3], v[150:153], v[138:141], v[0:3]
	s_setprio 0
.LBB0_70:
	s_barrier
	s_add_i32 s21, 0, 0x18000
	v_add_u32_e32 v80, s21, v239
	s_add_i32 s94, 0, 0x1c000
	ds_read_b128 v[154:157], v80
	ds_read_b128 v[158:161], v80 offset:1024
	ds_read_b128 v[162:165], v80 offset:2048
	ds_read_b128 v[166:169], v80 offset:3072
	v_add_u32_e32 v80, s94, v239
	ds_read_b128 v[130:133], v80
	ds_read_b128 v[142:145], v80 offset:1024
	ds_read_b128 v[146:149], v80 offset:2048
	ds_read_b128 v[150:153], v80 offset:3072
	s_and_b64 s[68:69], s[46:47], s[68:69]
	s_and_b64 s[68:69], s[68:69], exec
	s_cselect_b32 s69, s91, s10
	s_cselect_b32 s68, 0, 0
	s_add_u32 s66, s66, s69
	s_addc_u32 s67, s67, s68
	s_mov_b32 m0, s80
	s_waitcnt lgkmcnt(0)
	v_lshl_add_u64 v[134:135], s[66:67], 0, v[194:195]
	ds_read_b128 v[170:173], v241 offset:32768
	ds_read_b128 v[174:177], v241 offset:33792
	ds_read_b128 v[178:181], v241 offset:34816
	ds_read_b128 v[182:185], v241 offset:35840
	ds_read_b128 v[186:189], v241 offset:36864
	ds_read_b128 v[190:193], v241 offset:37888
	ds_read_b128 v[198:201], v241 offset:38912
	ds_read_b128 v[242:245], v241 offset:39936
	global_load_lds_dwordx4 v[134:135], off
	v_lshl_add_u64 v[134:135], s[66:67], 0, v[208:209]
	s_mov_b32 m0, s81
	s_nop 0
	global_load_lds_dwordx4 v[134:135], off
	s_waitcnt vmcnt(8)
	s_waitcnt lgkmcnt(0)
	s_barrier
	s_setprio 1
	s_waitcnt lgkmcnt(0)
	v_mfma_f32_16x16x32_bf16 v[114:117], v[154:157], v[170:173], v[114:117]
	v_mfma_f32_16x16x32_bf16 v[138:141], v[158:161], v[174:177], v[114:117]
	v_mfma_f32_16x16x32_bf16 v[114:117], v[162:165], v[170:173], v[126:129]
	v_mfma_f32_16x16x32_bf16 v[134:137], v[166:169], v[174:177], v[114:117]
	v_mfma_f32_16x16x32_bf16 v[114:117], v[154:157], v[178:181], v[122:125]
	v_mfma_f32_16x16x32_bf16 v[122:125], v[158:161], v[182:185], v[114:117]
	v_mfma_f32_16x16x32_bf16 v[114:117], v[162:165], v[178:181], v[118:121]
	v_mfma_f32_16x16x32_bf16 v[110:113], v[154:157], v[186:189], v[110:113]
	v_mfma_f32_16x16x32_bf16 v[106:109], v[162:165], v[186:189], v[106:109]
	v_mfma_f32_16x16x32_bf16 v[102:105], v[154:157], v[198:201], v[102:105]
	v_mfma_f32_16x16x32_bf16 v[98:101], v[162:165], v[198:201], v[98:101]
	v_mfma_f32_16x16x32_bf16 v[118:121], v[166:169], v[182:185], v[114:117]
	v_mfma_f32_16x16x32_bf16 v[110:113], v[158:161], v[190:193], v[110:113]
	v_mfma_f32_16x16x32_bf16 v[106:109], v[166:169], v[190:193], v[106:109]
	v_mfma_f32_16x16x32_bf16 v[102:105], v[158:161], v[242:245], v[102:105]
	v_mfma_f32_16x16x32_bf16 v[98:101], v[166:169], v[242:245], v[98:101]
	v_mfma_f32_16x16x32_bf16 v[86:89], v[130:133], v[170:173], v[86:89]
	v_mfma_f32_16x16x32_bf16 v[82:85], v[146:149], v[170:173], v[82:85]
	v_mfma_f32_16x16x32_bf16 v[68:71], v[130:133], v[178:181], v[68:71]
	v_mfma_f32_16x16x32_bf16 v[64:67], v[146:149], v[178:181], v[64:67]
	v_mfma_f32_16x16x32_bf16 v[52:55], v[130:133], v[186:189], v[52:55]
	v_mfma_f32_16x16x32_bf16 v[48:51], v[146:149], v[186:189], v[48:51]
	v_mfma_f32_16x16x32_bf16 v[36:39], v[130:133], v[198:201], v[36:39]
	v_mfma_f32_16x16x32_bf16 v[32:35], v[146:149], v[198:201], v[32:35]
	v_mfma_f32_16x16x32_bf16 v[86:89], v[142:145], v[174:177], v[86:89]
	v_mfma_f32_16x16x32_bf16 v[82:85], v[150:153], v[174:177], v[82:85]
	v_mfma_f32_16x16x32_bf16 v[68:71], v[142:145], v[182:185], v[68:71]
	v_mfma_f32_16x16x32_bf16 v[64:67], v[150:153], v[182:185], v[64:67]
	v_mfma_f32_16x16x32_bf16 v[52:55], v[142:145], v[190:193], v[52:55]
	v_mfma_f32_16x16x32_bf16 v[48:51], v[150:153], v[190:193], v[48:51]
	v_mfma_f32_16x16x32_bf16 v[36:39], v[142:145], v[242:245], v[36:39]
	v_mfma_f32_16x16x32_bf16 v[32:35], v[150:153], v[242:245], v[32:35]
	s_setprio 0
	s_barrier
	s_add_i32 s21, s21, s79
	v_lshl_add_u64 v[198:199], v[220:221], 0, s[18:19]
	s_mov_b32 m0, s21
	ds_read_b128 v[186:189], v241 offset:49152
	ds_read_b128 v[190:193], v241 offset:50176
	ds_read_b128 v[178:181], v241 offset:51200
	ds_read_b128 v[182:185], v241 offset:52224
	ds_read_b128 v[170:173], v241 offset:53248
	ds_read_b128 v[174:177], v241 offset:54272
	ds_read_b128 v[114:117], v241 offset:55296
	ds_read_b128 v[126:129], v241 offset:56320
	global_load_lds_dwordx4 v[198:199], off
	s_add_i32 m0, s21, 0x2000
	s_add_u32 s64, s64, 0x40080
	v_lshl_add_u64 v[198:199], v[222:223], 0, s[18:19]
	s_addc_u32 s65, s65, 0
	s_add_i32 s21, s94, s79
	global_load_lds_dwordx4 v[198:199], off
	v_lshl_add_u64 v[198:199], s[64:65], 0, v[206:207]
	s_mov_b32 m0, s21
	s_and_b64 vcc, exec, s[36:37]
	global_load_lds_dwordx4 v[198:199], off
	v_lshl_add_u64 v[198:199], s[64:65], 0, v[210:211]
	s_add_i32 m0, s21, 0x2000
	s_nop 0
	global_load_lds_dwordx4 v[198:199], off
	v_lshl_add_u64 v[198:199], v[224:225], 0, s[18:19]
	s_mov_b32 m0, s84
	s_nop 0
	global_load_lds_dwordx4 v[198:199], off
	v_lshl_add_u64 v[198:199], v[226:227], 0, s[18:19]
	s_mov_b32 m0, s85
	s_nop 0
	global_load_lds_dwordx4 v[198:199], off
	s_waitcnt vmcnt(8)
	s_waitcnt lgkmcnt(0)
	s_barrier
	s_cbranch_vccnz .LBB0_67
	s_setprio 1
	s_waitcnt lgkmcnt(0)
	v_mfma_f32_16x16x32_bf16 v[94:97], v[154:157], v[186:189], v[94:97]
	v_mfma_f32_16x16x32_bf16 v[90:93], v[162:165], v[186:189], v[90:93]
	v_mfma_f32_16x16x32_bf16 v[76:79], v[154:157], v[178:181], v[76:79]
	v_mfma_f32_16x16x32_bf16 v[72:75], v[162:165], v[178:181], v[72:75]
	v_mfma_f32_16x16x32_bf16 v[60:63], v[154:157], v[170:173], v[60:63]
	v_mfma_f32_16x16x32_bf16 v[56:59], v[162:165], v[170:173], v[56:59]
	v_mfma_f32_16x16x32_bf16 v[44:47], v[154:157], v[114:117], v[44:47]
	v_mfma_f32_16x16x32_bf16 v[40:43], v[162:165], v[114:117], v[40:43]
	v_mfma_f32_16x16x32_bf16 v[94:97], v[158:161], v[190:193], v[94:97]
	v_mfma_f32_16x16x32_bf16 v[90:93], v[166:169], v[190:193], v[90:93]
	v_mfma_f32_16x16x32_bf16 v[76:79], v[158:161], v[182:185], v[76:79]
	v_mfma_f32_16x16x32_bf16 v[72:75], v[166:169], v[182:185], v[72:75]
	v_mfma_f32_16x16x32_bf16 v[60:63], v[158:161], v[174:177], v[60:63]
	v_mfma_f32_16x16x32_bf16 v[56:59], v[166:169], v[174:177], v[56:59]
	v_mfma_f32_16x16x32_bf16 v[44:47], v[158:161], v[126:129], v[44:47]
	v_mfma_f32_16x16x32_bf16 v[40:43], v[166:169], v[126:129], v[40:43]
	v_mfma_f32_16x16x32_bf16 v[28:31], v[130:133], v[186:189], v[28:31]
	v_mfma_f32_16x16x32_bf16 v[24:27], v[146:149], v[186:189], v[24:27]
	v_mfma_f32_16x16x32_bf16 v[20:23], v[130:133], v[178:181], v[20:23]
	v_mfma_f32_16x16x32_bf16 v[16:19], v[146:149], v[178:181], v[16:19]
	v_mfma_f32_16x16x32_bf16 v[12:15], v[130:133], v[170:173], v[12:15]
	v_mfma_f32_16x16x32_bf16 v[8:11], v[146:149], v[170:173], v[8:11]
	v_mfma_f32_16x16x32_bf16 v[4:7], v[130:133], v[114:117], v[4:7]
	v_mfma_f32_16x16x32_bf16 v[0:3], v[146:149], v[114:117], v[0:3]
	v_mfma_f32_16x16x32_bf16 v[28:31], v[142:145], v[190:193], v[28:31]
	v_mfma_f32_16x16x32_bf16 v[24:27], v[150:153], v[190:193], v[24:27]
	v_mfma_f32_16x16x32_bf16 v[20:23], v[142:145], v[182:185], v[20:23]
	v_mfma_f32_16x16x32_bf16 v[16:19], v[150:153], v[182:185], v[16:19]
	v_mfma_f32_16x16x32_bf16 v[12:15], v[142:145], v[174:177], v[12:15]
	v_mfma_f32_16x16x32_bf16 v[8:11], v[150:153], v[174:177], v[8:11]
	v_mfma_f32_16x16x32_bf16 v[4:7], v[142:145], v[126:129], v[4:7]
	v_mfma_f32_16x16x32_bf16 v[0:3], v[150:153], v[126:129], v[0:3]
	s_setprio 0
	s_branch .LBB0_67

.LBB0_155:
	s_add_u32 s6, s2, 0x100
	s_addc_u32 s7, s3, 0
	s_add_i32 s42, 0, 0x10000
	s_cmp_eq_u32 s41, 2
	s_cselect_b32 s25, s97, s7
	s_cselect_b32 s24, s96, s6
	v_add_u32_e32 v140, s42, v155
	s_cselect_b32 s21, s5, s39
	s_cselect_b32 s20, s4, s38
	s_add_i32 s43, 0, 0x14000
	ds_read_b128 v[158:161], v140
	ds_read_b128 v[162:165], v140 offset:1024
	ds_read_b128 v[166:169], v140 offset:2048
	ds_read_b128 v[170:173], v140 offset:3072
	v_add_u32_e32 v140, s43, v155
	ds_read_b128 v[174:177], v140
	ds_read_b128 v[178:181], v140 offset:1024
	ds_read_b128 v[182:185], v140 offset:2048
	ds_read_b128 v[186:189], v140 offset:3072
	v_lshl_add_u64 v[140:141], s[2:3], 0, v[138:139]
	s_add_i32 m0, s65, 0xc000
	ds_read_b128 v[190:193], v157
	ds_read_b128 v[206:209], v157 offset:1024
	ds_read_b128 v[210:213], v157 offset:2048
	ds_read_b128 v[214:217], v157 offset:3072
	ds_read_b128 v[218:221], v157 offset:4096
	ds_read_b128 v[222:225], v157 offset:5120
	ds_read_b128 v[240:243], v157 offset:6144
	ds_read_b128 v[244:247], v157 offset:7168
	global_load_lds_dwordx4 v[140:141], off
	v_lshl_add_u64 v[140:141], s[2:3], 0, v[136:137]
	s_add_i32 m0, s65, 0xe000
	s_nop 0
	global_load_lds_dwordx4 v[140:141], off
	s_waitcnt vmcnt(8)
	s_waitcnt lgkmcnt(0)
	s_barrier
	s_setprio 1
	s_waitcnt lgkmcnt(0)
	v_mfma_f32_16x16x32_bf16 v[126:129], v[158:161], v[190:193], v[126:129]
	v_mfma_f32_16x16x32_bf16 v[122:125], v[166:169], v[190:193], v[122:125]
	v_mfma_f32_16x16x32_bf16 v[118:121], v[158:161], v[210:213], v[118:121]
	v_mfma_f32_16x16x32_bf16 v[114:117], v[166:169], v[210:213], v[114:117]
	v_mfma_f32_16x16x32_bf16 v[110:113], v[158:161], v[218:221], v[110:113]
	v_mfma_f32_16x16x32_bf16 v[106:109], v[166:169], v[218:221], v[106:109]
	v_mfma_f32_16x16x32_bf16 v[102:105], v[158:161], v[240:243], v[102:105]
	v_mfma_f32_16x16x32_bf16 v[98:101], v[166:169], v[240:243], v[98:101]
	v_mfma_f32_16x16x32_bf16 v[126:129], v[162:165], v[206:209], v[126:129]
	v_mfma_f32_16x16x32_bf16 v[122:125], v[170:173], v[206:209], v[122:125]
	v_mfma_f32_16x16x32_bf16 v[118:121], v[162:165], v[214:217], v[118:121]
	v_mfma_f32_16x16x32_bf16 v[114:117], v[170:173], v[214:217], v[114:117]
	v_mfma_f32_16x16x32_bf16 v[110:113], v[162:165], v[222:225], v[110:113]
	v_mfma_f32_16x16x32_bf16 v[106:109], v[170:173], v[222:225], v[106:109]
	v_mfma_f32_16x16x32_bf16 v[102:105], v[162:165], v[244:247], v[102:105]
	v_mfma_f32_16x16x32_bf16 v[98:101], v[170:173], v[244:247], v[98:101]
	v_mfma_f32_16x16x32_bf16 v[60:63], v[174:177], v[190:193], v[60:63]
	v_mfma_f32_16x16x32_bf16 v[56:59], v[182:185], v[190:193], v[56:59]
	v_mfma_f32_16x16x32_bf16 v[52:55], v[174:177], v[210:213], v[52:55]
	v_mfma_f32_16x16x32_bf16 v[48:51], v[182:185], v[210:213], v[48:51]
	v_mfma_f32_16x16x32_bf16 v[44:47], v[174:177], v[218:221], v[44:47]
	v_mfma_f32_16x16x32_bf16 v[40:43], v[182:185], v[218:221], v[40:43]
	v_mfma_f32_16x16x32_bf16 v[36:39], v[174:177], v[240:243], v[36:39]
	v_mfma_f32_16x16x32_bf16 v[32:35], v[182:185], v[240:243], v[32:35]
	v_mfma_f32_16x16x32_bf16 v[60:63], v[178:181], v[206:209], v[60:63]
	v_mfma_f32_16x16x32_bf16 v[56:59], v[186:189], v[206:209], v[56:59]
	v_mfma_f32_16x16x32_bf16 v[52:55], v[178:181], v[214:217], v[52:55]
	v_mfma_f32_16x16x32_bf16 v[48:51], v[186:189], v[214:217], v[48:51]
	v_mfma_f32_16x16x32_bf16 v[44:47], v[178:181], v[222:225], v[44:47]
	v_mfma_f32_16x16x32_bf16 v[40:43], v[186:189], v[222:225], v[40:43]
	v_mfma_f32_16x16x32_bf16 v[36:39], v[178:181], v[244:247], v[36:39]
	v_mfma_f32_16x16x32_bf16 v[32:35], v[186:189], v[244:247], v[32:35]
	s_setprio 0
	s_barrier
	s_add_i32 s2, s42, s64
	v_lshl_add_u64 v[140:141], s[20:21], 0, v[80:81]
	s_mov_b32 m0, s2
	ds_read_b128 v[190:193], v157 offset:16384
	ds_read_b128 v[206:209], v157 offset:17408
	ds_read_b128 v[210:213], v157 offset:18432
	ds_read_b128 v[214:217], v157 offset:19456
	ds_read_b128 v[218:221], v157 offset:20480
	ds_read_b128 v[222:225], v157 offset:21504
	ds_read_b128 v[240:243], v157 offset:22528
	ds_read_b128 v[244:247], v157 offset:23552
	global_load_lds_dwordx4 v[140:141], off
	s_add_i32 m0, s2, 0x2000
	s_add_u32 s2, s20, 0x18000
	v_lshl_add_u64 v[194:195], s[20:21], 0, v[134:135]
	s_addc_u32 s3, s21, 0
	s_add_i32 s42, s43, s64
	global_load_lds_dwordx4 v[194:195], off
	v_lshl_add_u64 v[198:199], s[2:3], 0, v[80:81]
	s_mov_b32 m0, s42
	v_lshl_add_u64 v[200:201], s[24:25], 0, v[132:133]
	global_load_lds_dwordx4 v[198:199], off
	v_lshl_add_u64 v[198:199], s[2:3], 0, v[134:135]
	s_add_i32 m0, s42, 0x2000
	s_nop 0
	global_load_lds_dwordx4 v[198:199], off
	v_lshl_add_u64 v[198:199], s[24:25], 0, v[130:131]
	s_mov_b32 m0, s65
	s_nop 0
	global_load_lds_dwordx4 v[198:199], off
	s_mov_b32 m0, s67
	s_nop 0
	global_load_lds_dwordx4 v[200:201], off
	s_waitcnt vmcnt(8)
	s_waitcnt lgkmcnt(0)
	s_barrier
	s_setprio 1
	s_waitcnt lgkmcnt(0)
	v_mfma_f32_16x16x32_bf16 v[94:97], v[158:161], v[190:193], v[94:97]
	v_mfma_f32_16x16x32_bf16 v[90:93], v[166:169], v[190:193], v[90:93]
	v_mfma_f32_16x16x32_bf16 v[86:89], v[158:161], v[210:213], v[86:89]
	v_mfma_f32_16x16x32_bf16 v[82:85], v[166:169], v[210:213], v[82:85]
	v_mfma_f32_16x16x32_bf16 v[76:79], v[158:161], v[218:221], v[76:79]
	v_mfma_f32_16x16x32_bf16 v[72:75], v[166:169], v[218:221], v[72:75]
	v_mfma_f32_16x16x32_bf16 v[68:71], v[158:161], v[240:243], v[68:71]
	v_mfma_f32_16x16x32_bf16 v[64:67], v[166:169], v[240:243], v[64:67]
	v_mfma_f32_16x16x32_bf16 v[94:97], v[162:165], v[206:209], v[94:97]
	v_mfma_f32_16x16x32_bf16 v[90:93], v[170:173], v[206:209], v[90:93]
	v_mfma_f32_16x16x32_bf16 v[86:89], v[162:165], v[214:217], v[86:89]
	v_mfma_f32_16x16x32_bf16 v[82:85], v[170:173], v[214:217], v[82:85]
	v_mfma_f32_16x16x32_bf16 v[76:79], v[162:165], v[222:225], v[76:79]
	v_mfma_f32_16x16x32_bf16 v[72:75], v[170:173], v[222:225], v[72:75]
	v_mfma_f32_16x16x32_bf16 v[68:71], v[162:165], v[244:247], v[68:71]
	v_mfma_f32_16x16x32_bf16 v[64:67], v[170:173], v[244:247], v[64:67]
	v_mfma_f32_16x16x32_bf16 v[28:31], v[174:177], v[190:193], v[28:31]
	v_mfma_f32_16x16x32_bf16 v[24:27], v[182:185], v[190:193], v[24:27]
	v_mfma_f32_16x16x32_bf16 v[20:23], v[174:177], v[210:213], v[20:23]
	v_mfma_f32_16x16x32_bf16 v[16:19], v[182:185], v[210:213], v[16:19]
	v_mfma_f32_16x16x32_bf16 v[12:15], v[174:177], v[218:221], v[12:15]
	v_mfma_f32_16x16x32_bf16 v[8:11], v[182:185], v[218:221], v[8:11]
	v_mfma_f32_16x16x32_bf16 v[4:7], v[174:177], v[240:243], v[4:7]
	v_mfma_f32_16x16x32_bf16 v[0:3], v[182:185], v[240:243], v[0:3]
	v_mfma_f32_16x16x32_bf16 v[28:31], v[178:181], v[206:209], v[28:31]
	v_mfma_f32_16x16x32_bf16 v[24:27], v[186:189], v[206:209], v[24:27]
	v_mfma_f32_16x16x32_bf16 v[20:23], v[178:181], v[214:217], v[20:23]
	v_mfma_f32_16x16x32_bf16 v[16:19], v[186:189], v[214:217], v[16:19]
	v_mfma_f32_16x16x32_bf16 v[12:15], v[178:181], v[222:225], v[12:15]
	v_mfma_f32_16x16x32_bf16 v[8:11], v[186:189], v[222:225], v[8:11]
	v_mfma_f32_16x16x32_bf16 v[4:7], v[178:181], v[244:247], v[4:7]
	v_mfma_f32_16x16x32_bf16 v[0:3], v[186:189], v[244:247], v[0:3]
	s_setprio 0
	s_barrier
	s_add_i32 s42, 0, 0x18000
	s_add_i32 s43, 0, 0x1c000
	v_add_u32_e32 v170, s42, v155
	v_add_u32_e32 v186, s43, v155
	ds_read_b128 v[158:161], v170
	ds_read_b128 v[162:165], v170 offset:1024
	ds_read_b128 v[166:169], v170 offset:2048
	ds_read_b128 v[170:173], v170 offset:3072
	ds_read_b128 v[174:177], v186
	ds_read_b128 v[178:181], v186 offset:1024
	ds_read_b128 v[182:185], v186 offset:2048
	ds_read_b128 v[186:189], v186 offset:3072
	s_add_u32 s2, s24, 0x18000
	s_addc_u32 s3, s25, 0
	s_mov_b32 m0, s68
	v_lshl_add_u64 v[202:203], s[2:3], 0, v[130:131]
	ds_read_b128 v[190:193], v157 offset:32768
	ds_read_b128 v[206:209], v157 offset:33792
	ds_read_b128 v[210:213], v157 offset:34816
	ds_read_b128 v[214:217], v157 offset:35840
	ds_read_b128 v[218:221], v157 offset:36864
	ds_read_b128 v[222:225], v157 offset:37888
	ds_read_b128 v[240:243], v157 offset:38912
	ds_read_b128 v[244:247], v157 offset:39936
	global_load_lds_dwordx4 v[202:203], off
	v_lshl_add_u64 v[202:203], s[2:3], 0, v[132:133]
	s_mov_b32 m0, s69
	s_nop 0
	global_load_lds_dwordx4 v[202:203], off
	s_waitcnt vmcnt(8)
	s_waitcnt lgkmcnt(0)
	s_barrier
	s_setprio 1
	s_waitcnt lgkmcnt(0)
	v_mfma_f32_16x16x32_bf16 v[126:129], v[158:161], v[190:193], v[126:129]
	v_mfma_f32_16x16x32_bf16 v[122:125], v[166:169], v[190:193], v[122:125]
	v_mfma_f32_16x16x32_bf16 v[118:121], v[158:161], v[210:213], v[118:121]
	v_mfma_f32_16x16x32_bf16 v[114:117], v[166:169], v[210:213], v[114:117]
	v_mfma_f32_16x16x32_bf16 v[110:113], v[158:161], v[218:221], v[110:113]
	v_mfma_f32_16x16x32_bf16 v[106:109], v[166:169], v[218:221], v[106:109]
	v_mfma_f32_16x16x32_bf16 v[102:105], v[158:161], v[240:243], v[102:105]
	v_mfma_f32_16x16x32_bf16 v[98:101], v[166:169], v[240:243], v[98:101]
	v_mfma_f32_16x16x32_bf16 v[126:129], v[162:165], v[206:209], v[126:129]
	v_mfma_f32_16x16x32_bf16 v[122:125], v[170:173], v[206:209], v[122:125]
	v_mfma_f32_16x16x32_bf16 v[118:121], v[162:165], v[214:217], v[118:121]
	v_mfma_f32_16x16x32_bf16 v[114:117], v[170:173], v[214:217], v[114:117]
	v_mfma_f32_16x16x32_bf16 v[110:113], v[162:165], v[222:225], v[110:113]
	v_mfma_f32_16x16x32_bf16 v[106:109], v[170:173], v[222:225], v[106:109]
	v_mfma_f32_16x16x32_bf16 v[102:105], v[162:165], v[244:247], v[102:105]
	v_mfma_f32_16x16x32_bf16 v[98:101], v[170:173], v[244:247], v[98:101]
	v_mfma_f32_16x16x32_bf16 v[60:63], v[174:177], v[190:193], v[60:63]
	v_mfma_f32_16x16x32_bf16 v[56:59], v[182:185], v[190:193], v[56:59]
	v_mfma_f32_16x16x32_bf16 v[52:55], v[174:177], v[210:213], v[52:55]
	v_mfma_f32_16x16x32_bf16 v[48:51], v[182:185], v[210:213], v[48:51]
	v_mfma_f32_16x16x32_bf16 v[44:47], v[174:177], v[218:221], v[44:47]
	v_mfma_f32_16x16x32_bf16 v[40:43], v[182:185], v[218:221], v[40:43]
	v_mfma_f32_16x16x32_bf16 v[36:39], v[174:177], v[240:243], v[36:39]
	v_mfma_f32_16x16x32_bf16 v[32:35], v[182:185], v[240:243], v[32:35]
	v_mfma_f32_16x16x32_bf16 v[60:63], v[178:181], v[206:209], v[60:63]
	v_mfma_f32_16x16x32_bf16 v[56:59], v[186:189], v[206:209], v[56:59]
	v_mfma_f32_16x16x32_bf16 v[52:55], v[178:181], v[214:217], v[52:55]
	v_mfma_f32_16x16x32_bf16 v[48:51], v[186:189], v[214:217], v[48:51]
	v_mfma_f32_16x16x32_bf16 v[44:47], v[178:181], v[222:225], v[44:47]
	v_mfma_f32_16x16x32_bf16 v[40:43], v[186:189], v[222:225], v[40:43]
	v_mfma_f32_16x16x32_bf16 v[36:39], v[178:181], v[244:247], v[36:39]
	v_mfma_f32_16x16x32_bf16 v[32:35], v[186:189], v[244:247], v[32:35]
	s_setprio 0
	s_barrier
	s_add_i32 s2, s42, s64
	v_lshl_add_u64 v[140:141], v[140:141], 0, s[18:19]
	s_mov_b32 m0, s2
	ds_read_b128 v[190:193], v157 offset:49152
	ds_read_b128 v[206:209], v157 offset:50176
	ds_read_b128 v[210:213], v157 offset:51200
	ds_read_b128 v[214:217], v157 offset:52224
	ds_read_b128 v[218:221], v157 offset:53248
	ds_read_b128 v[222:225], v157 offset:54272
	ds_read_b128 v[240:243], v157 offset:55296
	ds_read_b128 v[244:247], v157 offset:56320
	global_load_lds_dwordx4 v[140:141], off
	s_add_i32 m0, s2, 0x2000
	s_add_u32 s2, s20, 0x18080
	v_lshl_add_u64 v[140:141], v[194:195], 0, s[18:19]
	s_addc_u32 s3, s21, 0
	s_add_i32 s20, s43, s64
	global_load_lds_dwordx4 v[140:141], off
	v_lshl_add_u64 v[140:141], s[2:3], 0, v[80:81]
	s_mov_b32 m0, s20
	s_nop 0
	global_load_lds_dwordx4 v[140:141], off
	v_lshl_add_u64 v[140:141], s[2:3], 0, v[134:135]
	s_add_i32 m0, s20, 0x2000
	s_nop 0
	global_load_lds_dwordx4 v[140:141], off
	v_lshl_add_u64 v[140:141], v[198:199], 0, s[18:19]
	s_mov_b32 m0, s75
	s_nop 0
	global_load_lds_dwordx4 v[140:141], off
	v_lshl_add_u64 v[140:141], v[200:201], 0, s[18:19]
	s_mov_b32 m0, s76
	s_nop 0
	global_load_lds_dwordx4 v[140:141], off
	s_waitcnt vmcnt(8)
	s_waitcnt lgkmcnt(0)
	s_barrier
	s_setprio 1
	s_waitcnt lgkmcnt(0)
	v_mfma_f32_16x16x32_bf16 v[94:97], v[158:161], v[190:193], v[94:97]
	v_mfma_f32_16x16x32_bf16 v[90:93], v[166:169], v[190:193], v[90:93]
	v_mfma_f32_16x16x32_bf16 v[86:89], v[158:161], v[210:213], v[86:89]
	v_mfma_f32_16x16x32_bf16 v[82:85], v[166:169], v[210:213], v[82:85]
	v_mfma_f32_16x16x32_bf16 v[76:79], v[158:161], v[218:221], v[76:79]
	v_mfma_f32_16x16x32_bf16 v[72:75], v[166:169], v[218:221], v[72:75]
	v_mfma_f32_16x16x32_bf16 v[68:71], v[158:161], v[240:243], v[68:71]
	v_mfma_f32_16x16x32_bf16 v[64:67], v[166:169], v[240:243], v[64:67]
	v_mfma_f32_16x16x32_bf16 v[94:97], v[162:165], v[206:209], v[94:97]
	v_mfma_f32_16x16x32_bf16 v[90:93], v[170:173], v[206:209], v[90:93]
	v_mfma_f32_16x16x32_bf16 v[86:89], v[162:165], v[214:217], v[86:89]
	v_mfma_f32_16x16x32_bf16 v[82:85], v[170:173], v[214:217], v[82:85]
	v_mfma_f32_16x16x32_bf16 v[76:79], v[162:165], v[222:225], v[76:79]
	v_mfma_f32_16x16x32_bf16 v[72:75], v[170:173], v[222:225], v[72:75]
	v_mfma_f32_16x16x32_bf16 v[68:71], v[162:165], v[244:247], v[68:71]
	v_mfma_f32_16x16x32_bf16 v[64:67], v[170:173], v[244:247], v[64:67]
	v_mfma_f32_16x16x32_bf16 v[28:31], v[174:177], v[190:193], v[28:31]
	v_mfma_f32_16x16x32_bf16 v[24:27], v[182:185], v[190:193], v[24:27]
	v_mfma_f32_16x16x32_bf16 v[20:23], v[174:177], v[210:213], v[20:23]
	v_mfma_f32_16x16x32_bf16 v[16:19], v[182:185], v[210:213], v[16:19]
	v_mfma_f32_16x16x32_bf16 v[12:15], v[174:177], v[218:221], v[12:15]
	v_mfma_f32_16x16x32_bf16 v[8:11], v[182:185], v[218:221], v[8:11]
	v_mfma_f32_16x16x32_bf16 v[4:7], v[174:177], v[240:243], v[4:7]
	v_mfma_f32_16x16x32_bf16 v[0:3], v[182:185], v[240:243], v[0:3]
	v_mfma_f32_16x16x32_bf16 v[28:31], v[178:181], v[206:209], v[28:31]
	v_mfma_f32_16x16x32_bf16 v[24:27], v[186:189], v[206:209], v[24:27]
	v_mfma_f32_16x16x32_bf16 v[20:23], v[178:181], v[214:217], v[20:23]
	v_mfma_f32_16x16x32_bf16 v[16:19], v[186:189], v[214:217], v[16:19]
	v_mfma_f32_16x16x32_bf16 v[12:15], v[178:181], v[222:225], v[12:15]
	v_mfma_f32_16x16x32_bf16 v[8:11], v[186:189], v[222:225], v[8:11]
	v_mfma_f32_16x16x32_bf16 v[4:7], v[178:181], v[244:247], v[4:7]
	v_mfma_f32_16x16x32_bf16 v[0:3], v[186:189], v[244:247], v[0:3]
	s_setprio 0
	s_barrier
	s_add_i32 s41, s41, 2
	s_add_u32 s38, s38, 0x100
	s_addc_u32 s39, s39, 0
	s_cmp_gt_u32 s41, 3
	s_mov_b64 s[2:3], s[6:7]
	s_cbranch_scc0 .LBB0_155
	s_and_b64 vcc, exec, s[86:87]
	s_cbranch_vccz .LBB0_158
	s_barrier

.LBB0_203:
	s_add_u32 s4, s46, s52
	s_addc_u32 s5, s47, 0
	s_add_u32 s53, s4, 0x100
	s_addc_u32 s54, s5, 0
	s_and_b64 s[2:3], s[50:51], exec
	s_cselect_b32 s55, s25, s54
	s_cselect_b32 s54, s89, s53
	s_add_u32 s2, s44, s52
	s_addc_u32 s3, s45, 0
	s_add_u32 s52, s2, 0x100
	s_addc_u32 s53, s3, 0
	s_add_i32 s94, 0, 0x10000
	s_and_b64 s[2:3], s[50:51], exec
	s_cselect_b32 s57, s21, s53
	s_cselect_b32 s56, s90, s52
	s_add_i32 s51, 0, 0x14000
	s_add_u32 s64, s4, 0x10080
	s_addc_u32 s65, s5, 0
	s_add_i32 s3, s94, s76
	s_add_i32 m0, s43, 0xc000
	s_add_i32 s95, s43, 0xe000
	s_add_i32 vcc_lo, s3, 0x2000
	v_add_u32_e32 v151, s94, v147
	s_add_u32 s62, s56, 0x10000
	ds_read_b128 v[152:155], v151
	ds_read_b128 v[156:159], v151 offset:1024
	ds_read_b128 v[160:163], v151 offset:2048
	ds_read_b128 v[164:167], v151 offset:3072
	v_add_u32_e32 v151, s51, v147
	s_addc_u32 s63, s57, 0
	s_add_i32 vcc_hi, s51, s76
	ds_read_b128 v[168:171], v151
	ds_read_b128 v[172:175], v151 offset:1024
	ds_read_b128 v[176:179], v151 offset:2048
	ds_read_b128 v[180:183], v151 offset:3072
	s_add_i32 s2, vcc_hi, 0x2000
	s_add_i32 s97, 0, 0x18000
	s_add_i32 s96, 0, 0x1c000
	s_add_u32 s52, s54, 0x10000
	s_addc_u32 s53, s55, 0
	s_add_i32 s91, s97, s76
	s_add_i32 s72, s91, 0x2000
	s_add_u32 s50, s56, 0x10080
	s_addc_u32 s51, s57, 0
	s_add_i32 s5, s96, s76
	s_add_i32 s4, s5, 0x2000
	v_lshl_add_u64 v[198:199], s[64:65], 0, v[130:131]
	ds_read_b128 v[184:187], v148
	ds_read_b128 v[188:191], v148 offset:1024
	ds_read_b128 v[192:195], v148 offset:2048
	ds_read_b128 v[206:209], v148 offset:3072
	ds_read_b128 v[210:213], v148 offset:4096
	ds_read_b128 v[214:217], v148 offset:5120
	ds_read_b128 v[218:221], v148 offset:6144
	ds_read_b128 v[222:225], v148 offset:7168
	global_load_lds_dwordx4 v[198:199], off
	v_lshl_add_u64 v[198:199], s[64:65], 0, v[134:135]
	s_mov_b32 m0, s95
	s_nop 0
	global_load_lds_dwordx4 v[198:199], off
	s_waitcnt vmcnt(8)
	s_waitcnt lgkmcnt(0)
	s_barrier
	s_setprio 1
	s_waitcnt lgkmcnt(0)
	v_mfma_f32_16x16x32_bf16 v[126:129], v[152:155], v[184:187], v[126:129]
	v_mfma_f32_16x16x32_bf16 v[122:125], v[160:163], v[184:187], v[122:125]
	v_mfma_f32_16x16x32_bf16 v[118:121], v[152:155], v[192:195], v[118:121]
	v_mfma_f32_16x16x32_bf16 v[114:117], v[160:163], v[192:195], v[114:117]
	v_mfma_f32_16x16x32_bf16 v[110:113], v[152:155], v[210:213], v[110:113]
	v_mfma_f32_16x16x32_bf16 v[106:109], v[160:163], v[210:213], v[106:109]
	v_mfma_f32_16x16x32_bf16 v[102:105], v[152:155], v[218:221], v[102:105]
	v_mfma_f32_16x16x32_bf16 v[98:101], v[160:163], v[218:221], v[98:101]
	v_mfma_f32_16x16x32_bf16 v[126:129], v[156:159], v[188:191], v[126:129]
	v_mfma_f32_16x16x32_bf16 v[122:125], v[164:167], v[188:191], v[122:125]
	v_mfma_f32_16x16x32_bf16 v[118:121], v[156:159], v[206:209], v[118:121]
	v_mfma_f32_16x16x32_bf16 v[114:117], v[164:167], v[206:209], v[114:117]
	v_mfma_f32_16x16x32_bf16 v[110:113], v[156:159], v[214:217], v[110:113]
	v_mfma_f32_16x16x32_bf16 v[106:109], v[164:167], v[214:217], v[106:109]
	v_mfma_f32_16x16x32_bf16 v[102:105], v[156:159], v[222:225], v[102:105]
	v_mfma_f32_16x16x32_bf16 v[98:101], v[164:167], v[222:225], v[98:101]
	v_mfma_f32_16x16x32_bf16 v[76:79], v[168:171], v[184:187], v[76:79]
	v_mfma_f32_16x16x32_bf16 v[72:75], v[176:179], v[184:187], v[72:75]
	v_mfma_f32_16x16x32_bf16 v[60:63], v[168:171], v[192:195], v[60:63]
	v_mfma_f32_16x16x32_bf16 v[56:59], v[176:179], v[192:195], v[56:59]
	v_mfma_f32_16x16x32_bf16 v[44:47], v[168:171], v[210:213], v[44:47]
	v_mfma_f32_16x16x32_bf16 v[40:43], v[176:179], v[210:213], v[40:43]
	v_mfma_f32_16x16x32_bf16 v[36:39], v[168:171], v[218:221], v[36:39]
	v_mfma_f32_16x16x32_bf16 v[32:35], v[176:179], v[218:221], v[32:35]
	v_mfma_f32_16x16x32_bf16 v[76:79], v[172:175], v[188:191], v[76:79]
	v_mfma_f32_16x16x32_bf16 v[72:75], v[180:183], v[188:191], v[72:75]
	v_mfma_f32_16x16x32_bf16 v[60:63], v[172:175], v[206:209], v[60:63]
	v_mfma_f32_16x16x32_bf16 v[56:59], v[180:183], v[206:209], v[56:59]
	v_mfma_f32_16x16x32_bf16 v[44:47], v[172:175], v[214:217], v[44:47]
	v_mfma_f32_16x16x32_bf16 v[40:43], v[180:183], v[214:217], v[40:43]
	v_mfma_f32_16x16x32_bf16 v[36:39], v[172:175], v[222:225], v[36:39]
	v_mfma_f32_16x16x32_bf16 v[32:35], v[180:183], v[222:225], v[32:35]
	s_setprio 0
	s_barrier
	s_mov_b32 m0, s3
	v_lshl_add_u64 v[198:199], s[56:57], 0, v[132:133]
	ds_read_b128 v[184:187], v148 offset:16384
	ds_read_b128 v[188:191], v148 offset:17408
	ds_read_b128 v[192:195], v148 offset:18432
	ds_read_b128 v[206:209], v148 offset:19456
	ds_read_b128 v[210:213], v148 offset:20480
	ds_read_b128 v[214:217], v148 offset:21504
	ds_read_b128 v[218:221], v148 offset:22528
	ds_read_b128 v[222:225], v148 offset:23552
	global_load_lds_dwordx4 v[198:199], off
	v_lshl_add_u64 v[200:201], s[56:57], 0, v[136:137]
	s_mov_b32 m0, vcc_lo
	v_lshl_add_u64 v[202:203], s[62:63], 0, v[132:133]
	global_load_lds_dwordx4 v[200:201], off
	s_mov_b32 m0, vcc_hi
	v_lshl_add_u64 v[226:227], s[54:55], 0, v[134:135]
	global_load_lds_dwordx4 v[202:203], off
	v_lshl_add_u64 v[202:203], s[62:63], 0, v[136:137]
	s_mov_b32 m0, s2
	s_nop 0
	global_load_lds_dwordx4 v[202:203], off
	v_lshl_add_u64 v[202:203], s[54:55], 0, v[130:131]
	s_mov_b32 m0, s43
	s_nop 0
	global_load_lds_dwordx4 v[202:203], off
	s_mov_b32 m0, s78
	s_nop 0
	global_load_lds_dwordx4 v[226:227], off
	s_waitcnt vmcnt(8)
	s_waitcnt lgkmcnt(0)
	s_barrier
	s_setprio 1
	s_waitcnt lgkmcnt(0)
	v_mfma_f32_16x16x32_bf16 v[94:97], v[152:155], v[184:187], v[94:97]
	v_mfma_f32_16x16x32_bf16 v[90:93], v[160:163], v[184:187], v[90:93]
	v_mfma_f32_16x16x32_bf16 v[86:89], v[152:155], v[192:195], v[86:89]
	v_mfma_f32_16x16x32_bf16 v[82:85], v[160:163], v[192:195], v[82:85]
	v_mfma_f32_16x16x32_bf16 v[68:71], v[152:155], v[210:213], v[68:71]
	v_mfma_f32_16x16x32_bf16 v[64:67], v[160:163], v[210:213], v[64:67]
	v_mfma_f32_16x16x32_bf16 v[52:55], v[152:155], v[218:221], v[52:55]
	v_mfma_f32_16x16x32_bf16 v[48:51], v[160:163], v[218:221], v[48:51]
	v_mfma_f32_16x16x32_bf16 v[94:97], v[156:159], v[188:191], v[94:97]
	v_mfma_f32_16x16x32_bf16 v[90:93], v[164:167], v[188:191], v[90:93]
	v_mfma_f32_16x16x32_bf16 v[86:89], v[156:159], v[206:209], v[86:89]
	v_mfma_f32_16x16x32_bf16 v[82:85], v[164:167], v[206:209], v[82:85]
	v_mfma_f32_16x16x32_bf16 v[68:71], v[156:159], v[214:217], v[68:71]
	v_mfma_f32_16x16x32_bf16 v[64:67], v[164:167], v[214:217], v[64:67]
	v_mfma_f32_16x16x32_bf16 v[52:55], v[156:159], v[222:225], v[52:55]
	v_mfma_f32_16x16x32_bf16 v[48:51], v[164:167], v[222:225], v[48:51]
	v_mfma_f32_16x16x32_bf16 v[28:31], v[168:171], v[184:187], v[28:31]
	v_mfma_f32_16x16x32_bf16 v[24:27], v[176:179], v[184:187], v[24:27]
	v_mfma_f32_16x16x32_bf16 v[20:23], v[168:171], v[192:195], v[20:23]
	v_mfma_f32_16x16x32_bf16 v[16:19], v[176:179], v[192:195], v[16:19]
	v_mfma_f32_16x16x32_bf16 v[12:15], v[168:171], v[210:213], v[12:15]
	v_mfma_f32_16x16x32_bf16 v[8:11], v[176:179], v[210:213], v[8:11]
	v_mfma_f32_16x16x32_bf16 v[4:7], v[168:171], v[218:221], v[4:7]
	v_mfma_f32_16x16x32_bf16 v[0:3], v[176:179], v[218:221], v[0:3]
	v_mfma_f32_16x16x32_bf16 v[28:31], v[172:175], v[188:191], v[28:31]
	v_mfma_f32_16x16x32_bf16 v[24:27], v[180:183], v[188:191], v[24:27]
	v_mfma_f32_16x16x32_bf16 v[20:23], v[172:175], v[206:209], v[20:23]
	v_mfma_f32_16x16x32_bf16 v[16:19], v[180:183], v[206:209], v[16:19]
	v_mfma_f32_16x16x32_bf16 v[12:15], v[172:175], v[214:217], v[12:15]
	v_mfma_f32_16x16x32_bf16 v[8:11], v[180:183], v[214:217], v[8:11]
	v_mfma_f32_16x16x32_bf16 v[4:7], v[172:175], v[222:225], v[4:7]
	v_mfma_f32_16x16x32_bf16 v[0:3], v[180:183], v[222:225], v[0:3]
	s_setprio 0
	s_barrier
	v_add_u32_e32 v151, s97, v147
	ds_read_b128 v[152:155], v151
	ds_read_b128 v[156:159], v151 offset:1024
	ds_read_b128 v[160:163], v151 offset:2048
	ds_read_b128 v[164:167], v151 offset:3072
	v_add_u32_e32 v151, s96, v147
	ds_read_b128 v[168:171], v151
	ds_read_b128 v[172:175], v151 offset:1024
	ds_read_b128 v[176:179], v151 offset:2048
	ds_read_b128 v[180:183], v151 offset:3072
	s_mov_b32 m0, s79
	v_lshl_add_u64 v[240:241], s[52:53], 0, v[130:131]
	ds_read_b128 v[184:187], v148 offset:32768
	ds_read_b128 v[188:191], v148 offset:33792
	ds_read_b128 v[192:195], v148 offset:34816
	ds_read_b128 v[206:209], v148 offset:35840
	ds_read_b128 v[210:213], v148 offset:36864
	ds_read_b128 v[214:217], v148 offset:37888
	ds_read_b128 v[218:221], v148 offset:38912
	ds_read_b128 v[222:225], v148 offset:39936
	global_load_lds_dwordx4 v[240:241], off
	v_lshl_add_u64 v[240:241], s[52:53], 0, v[134:135]
	s_mov_b32 m0, s80
	s_nop 0
	global_load_lds_dwordx4 v[240:241], off
	s_waitcnt vmcnt(8)
	s_waitcnt lgkmcnt(0)
	s_barrier
	s_setprio 1
	s_waitcnt lgkmcnt(0)
	v_mfma_f32_16x16x32_bf16 v[126:129], v[152:155], v[184:187], v[126:129]
	v_mfma_f32_16x16x32_bf16 v[122:125], v[160:163], v[184:187], v[122:125]
	v_mfma_f32_16x16x32_bf16 v[118:121], v[152:155], v[192:195], v[118:121]
	v_mfma_f32_16x16x32_bf16 v[114:117], v[160:163], v[192:195], v[114:117]
	v_mfma_f32_16x16x32_bf16 v[110:113], v[152:155], v[210:213], v[110:113]
	v_mfma_f32_16x16x32_bf16 v[106:109], v[160:163], v[210:213], v[106:109]
	v_mfma_f32_16x16x32_bf16 v[102:105], v[152:155], v[218:221], v[102:105]
	v_mfma_f32_16x16x32_bf16 v[98:101], v[160:163], v[218:221], v[98:101]
	v_mfma_f32_16x16x32_bf16 v[126:129], v[156:159], v[188:191], v[126:129]
	v_mfma_f32_16x16x32_bf16 v[122:125], v[164:167], v[188:191], v[122:125]
	v_mfma_f32_16x16x32_bf16 v[118:121], v[156:159], v[206:209], v[118:121]
	v_mfma_f32_16x16x32_bf16 v[114:117], v[164:167], v[206:209], v[114:117]
	v_mfma_f32_16x16x32_bf16 v[110:113], v[156:159], v[214:217], v[110:113]
	v_mfma_f32_16x16x32_bf16 v[106:109], v[164:167], v[214:217], v[106:109]
	v_mfma_f32_16x16x32_bf16 v[102:105], v[156:159], v[222:225], v[102:105]
	v_mfma_f32_16x16x32_bf16 v[98:101], v[164:167], v[222:225], v[98:101]
	v_mfma_f32_16x16x32_bf16 v[76:79], v[168:171], v[184:187], v[76:79]
	v_mfma_f32_16x16x32_bf16 v[72:75], v[176:179], v[184:187], v[72:75]
	v_mfma_f32_16x16x32_bf16 v[60:63], v[168:171], v[192:195], v[60:63]
	v_mfma_f32_16x16x32_bf16 v[56:59], v[176:179], v[192:195], v[56:59]
	v_mfma_f32_16x16x32_bf16 v[44:47], v[168:171], v[210:213], v[44:47]
	v_mfma_f32_16x16x32_bf16 v[40:43], v[176:179], v[210:213], v[40:43]
	v_mfma_f32_16x16x32_bf16 v[36:39], v[168:171], v[218:221], v[36:39]
	v_mfma_f32_16x16x32_bf16 v[32:35], v[176:179], v[218:221], v[32:35]
	v_mfma_f32_16x16x32_bf16 v[76:79], v[172:175], v[188:191], v[76:79]
	v_mfma_f32_16x16x32_bf16 v[72:75], v[180:183], v[188:191], v[72:75]
	v_mfma_f32_16x16x32_bf16 v[60:63], v[172:175], v[206:209], v[60:63]
	v_mfma_f32_16x16x32_bf16 v[56:59], v[180:183], v[206:209], v[56:59]
	v_mfma_f32_16x16x32_bf16 v[44:47], v[172:175], v[214:217], v[44:47]
	v_mfma_f32_16x16x32_bf16 v[40:43], v[180:183], v[214:217], v[40:43]
	v_mfma_f32_16x16x32_bf16 v[36:39], v[172:175], v[222:225], v[36:39]
	v_mfma_f32_16x16x32_bf16 v[32:35], v[180:183], v[222:225], v[32:35]
	s_setprio 0
	s_barrier
	s_mov_b32 m0, s91
	v_lshl_add_u64 v[198:199], v[198:199], 0, s[18:19]
	ds_read_b128 v[184:187], v148 offset:49152
	ds_read_b128 v[188:191], v148 offset:50176
	ds_read_b128 v[192:195], v148 offset:51200
	ds_read_b128 v[206:209], v148 offset:52224
	ds_read_b128 v[210:213], v148 offset:53248
	ds_read_b128 v[214:217], v148 offset:54272
	ds_read_b128 v[218:221], v148 offset:55296
	ds_read_b128 v[222:225], v148 offset:56320
	global_load_lds_dwordx4 v[198:199], off
	v_lshl_add_u64 v[198:199], v[200:201], 0, s[18:19]
	s_mov_b32 m0, s72
	s_nop 0
	global_load_lds_dwordx4 v[198:199], off
	v_lshl_add_u64 v[198:199], s[50:51], 0, v[132:133]
	s_mov_b32 m0, s5
	s_nop 0
	global_load_lds_dwordx4 v[198:199], off
	v_lshl_add_u64 v[198:199], s[50:51], 0, v[136:137]
	s_mov_b32 m0, s4
	s_nop 0
	global_load_lds_dwordx4 v[198:199], off
	v_lshl_add_u64 v[198:199], v[202:203], 0, s[18:19]
	s_mov_b32 m0, s84
	s_nop 0
	global_load_lds_dwordx4 v[198:199], off
	v_lshl_add_u64 v[198:199], v[226:227], 0, s[18:19]
	s_mov_b32 m0, s85
	s_nop 0
	global_load_lds_dwordx4 v[198:199], off
	s_waitcnt vmcnt(8)
	s_waitcnt lgkmcnt(0)
	s_barrier
	s_setprio 1
	s_waitcnt lgkmcnt(0)
	v_mfma_f32_16x16x32_bf16 v[94:97], v[152:155], v[184:187], v[94:97]
	v_mfma_f32_16x16x32_bf16 v[90:93], v[160:163], v[184:187], v[90:93]
	v_mfma_f32_16x16x32_bf16 v[86:89], v[152:155], v[192:195], v[86:89]
	v_mfma_f32_16x16x32_bf16 v[82:85], v[160:163], v[192:195], v[82:85]
	v_mfma_f32_16x16x32_bf16 v[68:71], v[152:155], v[210:213], v[68:71]
	v_mfma_f32_16x16x32_bf16 v[64:67], v[160:163], v[210:213], v[64:67]
	v_mfma_f32_16x16x32_bf16 v[52:55], v[152:155], v[218:221], v[52:55]
	v_mfma_f32_16x16x32_bf16 v[48:51], v[160:163], v[218:221], v[48:51]
	v_mfma_f32_16x16x32_bf16 v[94:97], v[156:159], v[188:191], v[94:97]
	v_mfma_f32_16x16x32_bf16 v[90:93], v[164:167], v[188:191], v[90:93]
	v_mfma_f32_16x16x32_bf16 v[86:89], v[156:159], v[206:209], v[86:89]
	v_mfma_f32_16x16x32_bf16 v[82:85], v[164:167], v[206:209], v[82:85]
	v_mfma_f32_16x16x32_bf16 v[68:71], v[156:159], v[214:217], v[68:71]
	v_mfma_f32_16x16x32_bf16 v[64:67], v[164:167], v[214:217], v[64:67]
	v_mfma_f32_16x16x32_bf16 v[52:55], v[156:159], v[222:225], v[52:55]
	v_mfma_f32_16x16x32_bf16 v[48:51], v[164:167], v[222:225], v[48:51]
	v_mfma_f32_16x16x32_bf16 v[28:31], v[168:171], v[184:187], v[28:31]
	v_mfma_f32_16x16x32_bf16 v[24:27], v[176:179], v[184:187], v[24:27]
	v_mfma_f32_16x16x32_bf16 v[20:23], v[168:171], v[192:195], v[20:23]
	v_mfma_f32_16x16x32_bf16 v[16:19], v[176:179], v[192:195], v[16:19]
	v_mfma_f32_16x16x32_bf16 v[12:15], v[168:171], v[210:213], v[12:15]
	v_mfma_f32_16x16x32_bf16 v[8:11], v[176:179], v[210:213], v[8:11]
	v_mfma_f32_16x16x32_bf16 v[4:7], v[168:171], v[218:221], v[4:7]
	v_mfma_f32_16x16x32_bf16 v[0:3], v[176:179], v[218:221], v[0:3]
	v_mfma_f32_16x16x32_bf16 v[28:31], v[172:175], v[188:191], v[28:31]
	v_mfma_f32_16x16x32_bf16 v[24:27], v[180:183], v[188:191], v[24:27]
	v_mfma_f32_16x16x32_bf16 v[20:23], v[172:175], v[206:209], v[20:23]
	v_mfma_f32_16x16x32_bf16 v[16:19], v[180:183], v[206:209], v[16:19]
	v_mfma_f32_16x16x32_bf16 v[12:15], v[172:175], v[214:217], v[12:15]
	v_mfma_f32_16x16x32_bf16 v[8:11], v[180:183], v[214:217], v[8:11]
	v_mfma_f32_16x16x32_bf16 v[4:7], v[172:175], v[222:225], v[4:7]
	v_mfma_f32_16x16x32_bf16 v[0:3], v[180:183], v[222:225], v[0:3]
	s_setprio 0
	s_barrier
	s_movk_i32 s52, 0x100
	s_andn2_b64 vcc, exec, s[48:49]
	s_mov_b64 s[50:51], -1
	s_mov_b64 s[48:49], 0
	s_cbranch_vccz .LBB0_203
	s_and_b64 vcc, exec, s[8:9]
	s_cbranch_vccz .LBB0_206
	s_barrier

.LBB0_223:
	s_add_u32 s51, s42, s50
	s_addc_u32 s56, s43, 0
	s_add_u32 s54, s51, 0x100
	s_addc_u32 s55, s56, 0
	s_and_b64 s[52:53], s[48:49], exec
	s_cselect_b32 s53, s9, s55
	s_cselect_b32 s52, s21, s54
	s_add_u32 s50, s40, s50
	s_addc_u32 s54, s41, 0
	s_add_u32 s50, s50, 0x100
	s_addc_u32 s54, s54, 0
	s_add_i32 s91, 0, 0x10000
	s_and_b64 s[48:49], s[48:49], exec
	s_cselect_b32 s55, s7, s54
	s_cselect_b32 s54, s45, s50
	s_add_i32 s49, 0, 0x14000
	s_add_u32 s62, s51, 0x10080
	s_addc_u32 s63, s56, 0
	s_add_i32 s90, s91, s69
	s_add_i32 m0, s35, 0xc000
	s_add_i32 s94, s35, 0xe000
	s_add_i32 s87, s90, 0x2000
	v_add_u32_e32 v145, s91, v138
	s_add_u32 s56, s54, 0x10000
	ds_read_b128 v[150:153], v145
	ds_read_b128 v[154:157], v145 offset:1024
	ds_read_b128 v[158:161], v145 offset:2048
	ds_read_b128 v[162:165], v145 offset:3072
	v_add_u32_e32 v145, s49, v138
	s_addc_u32 s57, s55, 0
	s_add_i32 s89, s49, s69
	ds_read_b128 v[166:169], v145
	ds_read_b128 v[170:173], v145 offset:1024
	ds_read_b128 v[174:177], v145 offset:2048
	ds_read_b128 v[178:181], v145 offset:3072
	s_add_i32 s88, s89, 0x2000
	s_add_i32 s86, 0, 0x18000
	s_add_i32 s85, 0, 0x1c000
	s_add_u32 s50, s52, 0x10000
	s_addc_u32 s51, s53, 0
	s_add_i32 s84, s86, s69
	s_add_i32 s72, s84, 0x2000
	s_add_u32 s48, s54, 0x10080
	s_addc_u32 s49, s55, 0
	s_add_i32 s96, s85, s69
	s_add_i32 s91, s96, 0x2000
	v_lshl_add_u64 v[146:147], s[62:63], 0, v[130:131]
	ds_read_b128 v[182:185], v144
	ds_read_b128 v[186:189], v144 offset:1024
	ds_read_b128 v[190:193], v144 offset:2048
	ds_read_b128 v[206:209], v144 offset:3072
	ds_read_b128 v[210:213], v144 offset:4096
	ds_read_b128 v[214:217], v144 offset:5120
	ds_read_b128 v[218:221], v144 offset:6144
	ds_read_b128 v[222:225], v144 offset:7168
	global_load_lds_dwordx4 v[146:147], off
	v_lshl_add_u64 v[146:147], s[62:63], 0, v[134:135]
	s_mov_b32 m0, s94
	s_nop 0
	global_load_lds_dwordx4 v[146:147], off
	s_waitcnt vmcnt(8)
	s_waitcnt lgkmcnt(0)
	s_barrier
	s_setprio 1
	s_waitcnt lgkmcnt(0)
	v_mfma_f32_16x16x32_bf16 v[126:129], v[150:153], v[182:185], v[126:129]
	v_mfma_f32_16x16x32_bf16 v[122:125], v[158:161], v[182:185], v[122:125]
	v_mfma_f32_16x16x32_bf16 v[118:121], v[150:153], v[190:193], v[118:121]
	v_mfma_f32_16x16x32_bf16 v[114:117], v[158:161], v[190:193], v[114:117]
	v_mfma_f32_16x16x32_bf16 v[102:105], v[150:153], v[210:213], v[102:105]
	v_mfma_f32_16x16x32_bf16 v[98:101], v[158:161], v[210:213], v[98:101]
	v_mfma_f32_16x16x32_bf16 v[86:89], v[150:153], v[218:221], v[86:89]
	v_mfma_f32_16x16x32_bf16 v[82:85], v[158:161], v[218:221], v[82:85]
	v_mfma_f32_16x16x32_bf16 v[126:129], v[154:157], v[186:189], v[126:129]
	v_mfma_f32_16x16x32_bf16 v[122:125], v[162:165], v[186:189], v[122:125]
	v_mfma_f32_16x16x32_bf16 v[118:121], v[154:157], v[206:209], v[118:121]
	v_mfma_f32_16x16x32_bf16 v[114:117], v[162:165], v[206:209], v[114:117]
	v_mfma_f32_16x16x32_bf16 v[102:105], v[154:157], v[214:217], v[102:105]
	v_mfma_f32_16x16x32_bf16 v[98:101], v[162:165], v[214:217], v[98:101]
	v_mfma_f32_16x16x32_bf16 v[86:89], v[154:157], v[222:225], v[86:89]
	v_mfma_f32_16x16x32_bf16 v[82:85], v[162:165], v[222:225], v[82:85]
	v_mfma_f32_16x16x32_bf16 v[110:113], v[166:169], v[182:185], v[110:113]
	v_mfma_f32_16x16x32_bf16 v[106:109], v[174:177], v[182:185], v[106:109]
	v_mfma_f32_16x16x32_bf16 v[94:97], v[166:169], v[190:193], v[94:97]
	v_mfma_f32_16x16x32_bf16 v[90:93], v[174:177], v[190:193], v[90:93]
	v_mfma_f32_16x16x32_bf16 v[76:79], v[166:169], v[210:213], v[76:79]
	v_mfma_f32_16x16x32_bf16 v[72:75], v[174:177], v[210:213], v[72:75]
	v_mfma_f32_16x16x32_bf16 v[68:71], v[166:169], v[218:221], v[68:71]
	v_mfma_f32_16x16x32_bf16 v[64:67], v[174:177], v[218:221], v[64:67]
	v_mfma_f32_16x16x32_bf16 v[110:113], v[170:173], v[186:189], v[110:113]
	v_mfma_f32_16x16x32_bf16 v[106:109], v[178:181], v[186:189], v[106:109]
	v_mfma_f32_16x16x32_bf16 v[94:97], v[170:173], v[206:209], v[94:97]
	v_mfma_f32_16x16x32_bf16 v[90:93], v[178:181], v[206:209], v[90:93]
	v_mfma_f32_16x16x32_bf16 v[76:79], v[170:173], v[214:217], v[76:79]
	v_mfma_f32_16x16x32_bf16 v[72:75], v[178:181], v[214:217], v[72:75]
	v_mfma_f32_16x16x32_bf16 v[68:71], v[170:173], v[222:225], v[68:71]
	v_mfma_f32_16x16x32_bf16 v[64:67], v[178:181], v[222:225], v[64:67]
	s_setprio 0
	s_barrier
	s_mov_b32 m0, s90
	v_lshl_add_u64 v[146:147], s[54:55], 0, v[132:133]
	ds_read_b128 v[182:185], v144 offset:16384
	ds_read_b128 v[186:189], v144 offset:17408
	ds_read_b128 v[190:193], v144 offset:18432
	ds_read_b128 v[206:209], v144 offset:19456
	ds_read_b128 v[210:213], v144 offset:20480
	ds_read_b128 v[214:217], v144 offset:21504
	ds_read_b128 v[218:221], v144 offset:22528
	ds_read_b128 v[222:225], v144 offset:23552
	global_load_lds_dwordx4 v[146:147], off
	v_lshl_add_u64 v[194:195], s[54:55], 0, v[136:137]
	s_mov_b32 m0, s87
	v_lshl_add_u64 v[198:199], s[56:57], 0, v[132:133]
	global_load_lds_dwordx4 v[194:195], off
	s_mov_b32 m0, s89
	v_lshl_add_u64 v[200:201], s[52:53], 0, v[134:135]
	global_load_lds_dwordx4 v[198:199], off
	v_lshl_add_u64 v[198:199], s[56:57], 0, v[136:137]
	s_mov_b32 m0, s88
	s_nop 0
	global_load_lds_dwordx4 v[198:199], off
	v_lshl_add_u64 v[198:199], s[52:53], 0, v[130:131]
	s_mov_b32 m0, s35
	s_nop 0
	global_load_lds_dwordx4 v[198:199], off
	s_mov_b32 m0, s75
	s_nop 0
	global_load_lds_dwordx4 v[200:201], off
	s_waitcnt vmcnt(8)
	s_waitcnt lgkmcnt(0)
	s_barrier
	s_setprio 1
	s_waitcnt lgkmcnt(0)
	v_mfma_f32_16x16x32_bf16 v[60:63], v[150:153], v[182:185], v[60:63]
	v_mfma_f32_16x16x32_bf16 v[56:59], v[158:161], v[182:185], v[56:59]
	v_mfma_f32_16x16x32_bf16 v[52:55], v[150:153], v[190:193], v[52:55]
	v_mfma_f32_16x16x32_bf16 v[48:51], v[158:161], v[190:193], v[48:51]
	v_mfma_f32_16x16x32_bf16 v[36:39], v[150:153], v[210:213], v[36:39]
	v_mfma_f32_16x16x32_bf16 v[32:35], v[158:161], v[210:213], v[32:35]
	v_mfma_f32_16x16x32_bf16 v[20:23], v[150:153], v[218:221], v[20:23]
	v_mfma_f32_16x16x32_bf16 v[16:19], v[158:161], v[218:221], v[16:19]
	v_mfma_f32_16x16x32_bf16 v[60:63], v[154:157], v[186:189], v[60:63]
	v_mfma_f32_16x16x32_bf16 v[56:59], v[162:165], v[186:189], v[56:59]
	v_mfma_f32_16x16x32_bf16 v[52:55], v[154:157], v[206:209], v[52:55]
	v_mfma_f32_16x16x32_bf16 v[48:51], v[162:165], v[206:209], v[48:51]
	v_mfma_f32_16x16x32_bf16 v[36:39], v[154:157], v[214:217], v[36:39]
	v_mfma_f32_16x16x32_bf16 v[32:35], v[162:165], v[214:217], v[32:35]
	v_mfma_f32_16x16x32_bf16 v[20:23], v[154:157], v[222:225], v[20:23]
	v_mfma_f32_16x16x32_bf16 v[16:19], v[162:165], v[222:225], v[16:19]
	v_mfma_f32_16x16x32_bf16 v[44:47], v[166:169], v[182:185], v[44:47]
	v_mfma_f32_16x16x32_bf16 v[40:43], v[174:177], v[182:185], v[40:43]
	v_mfma_f32_16x16x32_bf16 v[28:31], v[166:169], v[190:193], v[28:31]
	v_mfma_f32_16x16x32_bf16 v[24:27], v[174:177], v[190:193], v[24:27]
	v_mfma_f32_16x16x32_bf16 v[12:15], v[166:169], v[210:213], v[12:15]
	v_mfma_f32_16x16x32_bf16 v[8:11], v[174:177], v[210:213], v[8:11]
	v_mfma_f32_16x16x32_bf16 v[4:7], v[166:169], v[218:221], v[4:7]
	v_mfma_f32_16x16x32_bf16 v[0:3], v[174:177], v[218:221], v[0:3]
	v_mfma_f32_16x16x32_bf16 v[44:47], v[170:173], v[186:189], v[44:47]
	v_mfma_f32_16x16x32_bf16 v[40:43], v[178:181], v[186:189], v[40:43]
	v_mfma_f32_16x16x32_bf16 v[28:31], v[170:173], v[206:209], v[28:31]
	v_mfma_f32_16x16x32_bf16 v[24:27], v[178:181], v[206:209], v[24:27]
	v_mfma_f32_16x16x32_bf16 v[12:15], v[170:173], v[214:217], v[12:15]
	v_mfma_f32_16x16x32_bf16 v[8:11], v[178:181], v[214:217], v[8:11]
	v_mfma_f32_16x16x32_bf16 v[4:7], v[170:173], v[222:225], v[4:7]
	v_mfma_f32_16x16x32_bf16 v[0:3], v[178:181], v[222:225], v[0:3]
	s_setprio 0
	s_barrier
	v_add_u32_e32 v145, s86, v138
	ds_read_b128 v[150:153], v145
	ds_read_b128 v[154:157], v145 offset:1024
	ds_read_b128 v[158:161], v145 offset:2048
	ds_read_b128 v[162:165], v145 offset:3072
	v_add_u32_e32 v145, s85, v138
	ds_read_b128 v[166:169], v145
	ds_read_b128 v[170:173], v145 offset:1024
	ds_read_b128 v[174:177], v145 offset:2048
	ds_read_b128 v[178:181], v145 offset:3072
	s_mov_b32 m0, s76
	v_lshl_add_u64 v[202:203], s[50:51], 0, v[130:131]
	ds_read_b128 v[182:185], v144 offset:32768
	ds_read_b128 v[186:189], v144 offset:33792
	ds_read_b128 v[190:193], v144 offset:34816
	ds_read_b128 v[206:209], v144 offset:35840
	ds_read_b128 v[210:213], v144 offset:36864
	ds_read_b128 v[214:217], v144 offset:37888
	ds_read_b128 v[218:221], v144 offset:38912
	ds_read_b128 v[222:225], v144 offset:39936
	global_load_lds_dwordx4 v[202:203], off
	v_lshl_add_u64 v[202:203], s[50:51], 0, v[134:135]
	s_mov_b32 m0, s77
	s_nop 0
	global_load_lds_dwordx4 v[202:203], off
	s_waitcnt vmcnt(8)
	s_waitcnt lgkmcnt(0)
	s_barrier
	s_setprio 1
	s_waitcnt lgkmcnt(0)
	v_mfma_f32_16x16x32_bf16 v[126:129], v[150:153], v[182:185], v[126:129]
	v_mfma_f32_16x16x32_bf16 v[122:125], v[158:161], v[182:185], v[122:125]
	v_mfma_f32_16x16x32_bf16 v[118:121], v[150:153], v[190:193], v[118:121]
	v_mfma_f32_16x16x32_bf16 v[114:117], v[158:161], v[190:193], v[114:117]
	v_mfma_f32_16x16x32_bf16 v[102:105], v[150:153], v[210:213], v[102:105]
	v_mfma_f32_16x16x32_bf16 v[98:101], v[158:161], v[210:213], v[98:101]
	v_mfma_f32_16x16x32_bf16 v[86:89], v[150:153], v[218:221], v[86:89]
	v_mfma_f32_16x16x32_bf16 v[82:85], v[158:161], v[218:221], v[82:85]
	v_mfma_f32_16x16x32_bf16 v[126:129], v[154:157], v[186:189], v[126:129]
	v_mfma_f32_16x16x32_bf16 v[122:125], v[162:165], v[186:189], v[122:125]
	v_mfma_f32_16x16x32_bf16 v[118:121], v[154:157], v[206:209], v[118:121]
	v_mfma_f32_16x16x32_bf16 v[114:117], v[162:165], v[206:209], v[114:117]
	v_mfma_f32_16x16x32_bf16 v[102:105], v[154:157], v[214:217], v[102:105]
	v_mfma_f32_16x16x32_bf16 v[98:101], v[162:165], v[214:217], v[98:101]
	v_mfma_f32_16x16x32_bf16 v[86:89], v[154:157], v[222:225], v[86:89]
	v_mfma_f32_16x16x32_bf16 v[82:85], v[162:165], v[222:225], v[82:85]
	v_mfma_f32_16x16x32_bf16 v[110:113], v[166:169], v[182:185], v[110:113]
	v_mfma_f32_16x16x32_bf16 v[106:109], v[174:177], v[182:185], v[106:109]
	v_mfma_f32_16x16x32_bf16 v[94:97], v[166:169], v[190:193], v[94:97]
	v_mfma_f32_16x16x32_bf16 v[90:93], v[174:177], v[190:193], v[90:93]
	v_mfma_f32_16x16x32_bf16 v[76:79], v[166:169], v[210:213], v[76:79]
	v_mfma_f32_16x16x32_bf16 v[72:75], v[174:177], v[210:213], v[72:75]
	v_mfma_f32_16x16x32_bf16 v[68:71], v[166:169], v[218:221], v[68:71]
	v_mfma_f32_16x16x32_bf16 v[64:67], v[174:177], v[218:221], v[64:67]
	v_mfma_f32_16x16x32_bf16 v[110:113], v[170:173], v[186:189], v[110:113]
	v_mfma_f32_16x16x32_bf16 v[106:109], v[178:181], v[186:189], v[106:109]
	v_mfma_f32_16x16x32_bf16 v[94:97], v[170:173], v[206:209], v[94:97]
	v_mfma_f32_16x16x32_bf16 v[90:93], v[178:181], v[206:209], v[90:93]
	v_mfma_f32_16x16x32_bf16 v[76:79], v[170:173], v[214:217], v[76:79]
	v_mfma_f32_16x16x32_bf16 v[72:75], v[178:181], v[214:217], v[72:75]
	v_mfma_f32_16x16x32_bf16 v[68:71], v[170:173], v[222:225], v[68:71]
	v_mfma_f32_16x16x32_bf16 v[64:67], v[178:181], v[222:225], v[64:67]
	s_setprio 0
	s_barrier
	s_mov_b32 m0, s84
	v_lshl_add_u64 v[146:147], v[146:147], 0, s[18:19]
	ds_read_b128 v[182:185], v144 offset:49152
	ds_read_b128 v[186:189], v144 offset:50176
	ds_read_b128 v[190:193], v144 offset:51200
	ds_read_b128 v[206:209], v144 offset:52224
	ds_read_b128 v[210:213], v144 offset:53248
	ds_read_b128 v[214:217], v144 offset:54272
	ds_read_b128 v[218:221], v144 offset:55296
	ds_read_b128 v[222:225], v144 offset:56320
	global_load_lds_dwordx4 v[146:147], off
	v_lshl_add_u64 v[146:147], v[194:195], 0, s[18:19]
	s_mov_b32 m0, s72
	s_nop 0
	global_load_lds_dwordx4 v[146:147], off
	v_lshl_add_u64 v[146:147], s[48:49], 0, v[132:133]
	s_mov_b32 m0, s96
	s_nop 0
	global_load_lds_dwordx4 v[146:147], off
	v_lshl_add_u64 v[146:147], s[48:49], 0, v[136:137]
	s_mov_b32 m0, s91
	s_nop 0
	global_load_lds_dwordx4 v[146:147], off
	v_lshl_add_u64 v[146:147], v[198:199], 0, s[18:19]
	s_mov_b32 m0, s80
	s_nop 0
	global_load_lds_dwordx4 v[146:147], off
	v_lshl_add_u64 v[146:147], v[200:201], 0, s[18:19]
	s_mov_b32 m0, s81
	s_nop 0
	global_load_lds_dwordx4 v[146:147], off
	s_waitcnt vmcnt(8)
	s_waitcnt lgkmcnt(0)
	s_barrier
	s_setprio 1
	s_waitcnt lgkmcnt(0)
	v_mfma_f32_16x16x32_bf16 v[60:63], v[150:153], v[182:185], v[60:63]
	v_mfma_f32_16x16x32_bf16 v[56:59], v[158:161], v[182:185], v[56:59]
	v_mfma_f32_16x16x32_bf16 v[52:55], v[150:153], v[190:193], v[52:55]
	v_mfma_f32_16x16x32_bf16 v[48:51], v[158:161], v[190:193], v[48:51]
	v_mfma_f32_16x16x32_bf16 v[36:39], v[150:153], v[210:213], v[36:39]
	v_mfma_f32_16x16x32_bf16 v[32:35], v[158:161], v[210:213], v[32:35]
	v_mfma_f32_16x16x32_bf16 v[20:23], v[150:153], v[218:221], v[20:23]
	v_mfma_f32_16x16x32_bf16 v[16:19], v[158:161], v[218:221], v[16:19]
	v_mfma_f32_16x16x32_bf16 v[60:63], v[154:157], v[186:189], v[60:63]
	v_mfma_f32_16x16x32_bf16 v[56:59], v[162:165], v[186:189], v[56:59]
	v_mfma_f32_16x16x32_bf16 v[52:55], v[154:157], v[206:209], v[52:55]
	v_mfma_f32_16x16x32_bf16 v[48:51], v[162:165], v[206:209], v[48:51]
	v_mfma_f32_16x16x32_bf16 v[36:39], v[154:157], v[214:217], v[36:39]
	v_mfma_f32_16x16x32_bf16 v[32:35], v[162:165], v[214:217], v[32:35]
	v_mfma_f32_16x16x32_bf16 v[20:23], v[154:157], v[222:225], v[20:23]
	v_mfma_f32_16x16x32_bf16 v[16:19], v[162:165], v[222:225], v[16:19]
	v_mfma_f32_16x16x32_bf16 v[44:47], v[166:169], v[182:185], v[44:47]
	v_mfma_f32_16x16x32_bf16 v[40:43], v[174:177], v[182:185], v[40:43]
	v_mfma_f32_16x16x32_bf16 v[28:31], v[166:169], v[190:193], v[28:31]
	v_mfma_f32_16x16x32_bf16 v[24:27], v[174:177], v[190:193], v[24:27]
	v_mfma_f32_16x16x32_bf16 v[12:15], v[166:169], v[210:213], v[12:15]
	v_mfma_f32_16x16x32_bf16 v[8:11], v[174:177], v[210:213], v[8:11]
	v_mfma_f32_16x16x32_bf16 v[4:7], v[166:169], v[218:221], v[4:7]
	v_mfma_f32_16x16x32_bf16 v[0:3], v[174:177], v[218:221], v[0:3]
	v_mfma_f32_16x16x32_bf16 v[44:47], v[170:173], v[186:189], v[44:47]
	v_mfma_f32_16x16x32_bf16 v[40:43], v[178:181], v[186:189], v[40:43]
	v_mfma_f32_16x16x32_bf16 v[28:31], v[170:173], v[206:209], v[28:31]
	v_mfma_f32_16x16x32_bf16 v[24:27], v[178:181], v[206:209], v[24:27]
	v_mfma_f32_16x16x32_bf16 v[12:15], v[170:173], v[214:217], v[12:15]
	v_mfma_f32_16x16x32_bf16 v[8:11], v[178:181], v[214:217], v[8:11]
	v_mfma_f32_16x16x32_bf16 v[4:7], v[170:173], v[222:225], v[4:7]
	v_mfma_f32_16x16x32_bf16 v[0:3], v[178:181], v[222:225], v[0:3]
	s_setprio 0
	s_barrier
	s_movk_i32 s50, 0x100
	s_andn2_b64 vcc, exec, s[46:47]
	s_mov_b64 s[48:49], -1
	s_mov_b64 s[46:47], 0
	s_cbranch_vccz .LBB0_223
	s_and_b64 vcc, exec, s[4:5]
	s_cbranch_vccz .LBB0_226
	s_barrier

.LBB0_338:
	s_add_u32 s24, s20, 0xfffc0080
	s_addc_u32 s25, s21, -1
	s_add_i32 s72, 0, 0x10000
	s_cmp_eq_u32 s74, 12
	s_cselect_b32 s39, s3, s25
	s_cselect_b32 s38, s35, s24
	s_cselect_b32 s25, s43, s69
	s_cselect_b32 s24, s45, s68
	s_add_i32 s75, 0, 0x14000
	v_add_u32_e32 v156, s72, v145
	v_add_u32_e32 v172, s75, v145
	ds_read_b128 v[140:143], v156
	ds_read_b128 v[148:151], v156 offset:1024
	ds_read_b128 v[152:155], v156 offset:2048
	ds_read_b128 v[156:159], v156 offset:3072
	ds_read_b128 v[160:163], v172
	ds_read_b128 v[164:167], v172 offset:1024
	ds_read_b128 v[168:171], v172 offset:2048
	ds_read_b128 v[172:175], v172 offset:3072
	v_lshl_add_u64 v[198:199], s[20:21], 0, v[138:139]
	s_add_i32 m0, s7, 0xc000
	ds_read_b128 v[176:179], v147
	ds_read_b128 v[180:183], v147 offset:1024
	ds_read_b128 v[184:187], v147 offset:2048
	ds_read_b128 v[188:191], v147 offset:3072
	ds_read_b128 v[192:195], v147 offset:4096
	ds_read_b128 v[206:209], v147 offset:5120
	ds_read_b128 v[210:213], v147 offset:6144
	ds_read_b128 v[214:217], v147 offset:7168
	global_load_lds_dwordx4 v[198:199], off
	v_lshl_add_u64 v[198:199], s[20:21], 0, v[136:137]
	s_add_i32 m0, s7, 0xe000
	s_nop 0
	global_load_lds_dwordx4 v[198:199], off
	s_waitcnt vmcnt(8)
	s_waitcnt lgkmcnt(0)
	s_barrier
	s_setprio 1
	s_waitcnt lgkmcnt(0)
	v_mfma_f32_16x16x32_bf16 v[126:129], v[140:143], v[176:179], v[126:129]
	v_mfma_f32_16x16x32_bf16 v[122:125], v[152:155], v[176:179], v[122:125]
	v_mfma_f32_16x16x32_bf16 v[110:113], v[140:143], v[184:187], v[110:113]
	v_mfma_f32_16x16x32_bf16 v[106:109], v[152:155], v[184:187], v[106:109]
	v_mfma_f32_16x16x32_bf16 v[94:97], v[140:143], v[192:195], v[94:97]
	v_mfma_f32_16x16x32_bf16 v[90:93], v[152:155], v[192:195], v[90:93]
	v_mfma_f32_16x16x32_bf16 v[76:79], v[140:143], v[210:213], v[76:79]
	v_mfma_f32_16x16x32_bf16 v[72:75], v[152:155], v[210:213], v[72:75]
	v_mfma_f32_16x16x32_bf16 v[126:129], v[148:151], v[180:183], v[126:129]
	v_mfma_f32_16x16x32_bf16 v[122:125], v[156:159], v[180:183], v[122:125]
	v_mfma_f32_16x16x32_bf16 v[110:113], v[148:151], v[188:191], v[110:113]
	v_mfma_f32_16x16x32_bf16 v[106:109], v[156:159], v[188:191], v[106:109]
	v_mfma_f32_16x16x32_bf16 v[94:97], v[148:151], v[206:209], v[94:97]
	v_mfma_f32_16x16x32_bf16 v[90:93], v[156:159], v[206:209], v[90:93]
	v_mfma_f32_16x16x32_bf16 v[76:79], v[148:151], v[214:217], v[76:79]
	v_mfma_f32_16x16x32_bf16 v[72:75], v[156:159], v[214:217], v[72:75]
	v_mfma_f32_16x16x32_bf16 v[118:121], v[160:163], v[176:179], v[118:121]
	v_mfma_f32_16x16x32_bf16 v[114:117], v[168:171], v[176:179], v[114:117]
	v_mfma_f32_16x16x32_bf16 v[102:105], v[160:163], v[184:187], v[102:105]
	v_mfma_f32_16x16x32_bf16 v[98:101], v[168:171], v[184:187], v[98:101]
	v_mfma_f32_16x16x32_bf16 v[86:89], v[160:163], v[192:195], v[86:89]
	v_mfma_f32_16x16x32_bf16 v[82:85], v[168:171], v[192:195], v[82:85]
	v_mfma_f32_16x16x32_bf16 v[68:71], v[160:163], v[210:213], v[68:71]
	v_mfma_f32_16x16x32_bf16 v[64:67], v[168:171], v[210:213], v[64:67]
	v_mfma_f32_16x16x32_bf16 v[118:121], v[164:167], v[180:183], v[118:121]
	v_mfma_f32_16x16x32_bf16 v[114:117], v[172:175], v[180:183], v[114:117]
	v_mfma_f32_16x16x32_bf16 v[102:105], v[164:167], v[188:191], v[102:105]
	v_mfma_f32_16x16x32_bf16 v[98:101], v[172:175], v[188:191], v[98:101]
	v_mfma_f32_16x16x32_bf16 v[86:89], v[164:167], v[206:209], v[86:89]
	v_mfma_f32_16x16x32_bf16 v[82:85], v[172:175], v[206:209], v[82:85]
	v_mfma_f32_16x16x32_bf16 v[68:71], v[164:167], v[214:217], v[68:71]
	v_mfma_f32_16x16x32_bf16 v[64:67], v[172:175], v[214:217], v[64:67]
	s_setprio 0
	s_barrier
	s_add_i32 s72, s72, s55
	v_lshl_add_u64 v[198:199], s[24:25], 0, v[80:81]
	s_mov_b32 m0, s72
	ds_read_b128 v[176:179], v147 offset:16384
	ds_read_b128 v[180:183], v147 offset:17408
	ds_read_b128 v[184:187], v147 offset:18432
	ds_read_b128 v[188:191], v147 offset:19456
	ds_read_b128 v[192:195], v147 offset:20480
	ds_read_b128 v[206:209], v147 offset:21504
	ds_read_b128 v[210:213], v147 offset:22528
	ds_read_b128 v[214:217], v147 offset:23552
	global_load_lds_dwordx4 v[198:199], off
	s_add_i32 m0, s72, 0x2000
	s_add_u32 s76, s24, 0x40000
	v_lshl_add_u64 v[200:201], s[24:25], 0, v[134:135]
	s_addc_u32 s77, s25, 0
	s_add_i32 s72, s75, s55
	global_load_lds_dwordx4 v[200:201], off
	v_lshl_add_u64 v[202:203], s[76:77], 0, v[80:81]
	s_mov_b32 m0, s72
	v_lshl_add_u64 v[218:219], s[38:39], 0, v[132:133]
	global_load_lds_dwordx4 v[202:203], off
	v_lshl_add_u64 v[202:203], s[76:77], 0, v[134:135]
	s_add_i32 m0, s72, 0x2000
	s_nop 0
	global_load_lds_dwordx4 v[202:203], off
	v_lshl_add_u64 v[202:203], s[38:39], 0, v[130:131]
	s_mov_b32 m0, s7
	s_nop 0
	global_load_lds_dwordx4 v[202:203], off
	s_mov_b32 m0, s56
	s_nop 0
	global_load_lds_dwordx4 v[218:219], off
	s_waitcnt vmcnt(8)
	s_waitcnt lgkmcnt(0)
	s_barrier
	s_setprio 1
	s_waitcnt lgkmcnt(0)
	v_mfma_f32_16x16x32_bf16 v[60:63], v[140:143], v[176:179], v[60:63]
	v_mfma_f32_16x16x32_bf16 v[56:59], v[152:155], v[176:179], v[56:59]
	v_mfma_f32_16x16x32_bf16 v[44:47], v[140:143], v[184:187], v[44:47]
	v_mfma_f32_16x16x32_bf16 v[40:43], v[152:155], v[184:187], v[40:43]
	v_mfma_f32_16x16x32_bf16 v[28:31], v[140:143], v[192:195], v[28:31]
	v_mfma_f32_16x16x32_bf16 v[24:27], v[152:155], v[192:195], v[24:27]
	v_mfma_f32_16x16x32_bf16 v[12:15], v[140:143], v[210:213], v[12:15]
	v_mfma_f32_16x16x32_bf16 v[8:11], v[152:155], v[210:213], v[8:11]
	v_mfma_f32_16x16x32_bf16 v[60:63], v[148:151], v[180:183], v[60:63]
	v_mfma_f32_16x16x32_bf16 v[56:59], v[156:159], v[180:183], v[56:59]
	v_mfma_f32_16x16x32_bf16 v[44:47], v[148:151], v[188:191], v[44:47]
	v_mfma_f32_16x16x32_bf16 v[40:43], v[156:159], v[188:191], v[40:43]
	v_mfma_f32_16x16x32_bf16 v[28:31], v[148:151], v[206:209], v[28:31]
	v_mfma_f32_16x16x32_bf16 v[24:27], v[156:159], v[206:209], v[24:27]
	v_mfma_f32_16x16x32_bf16 v[12:15], v[148:151], v[214:217], v[12:15]
	v_mfma_f32_16x16x32_bf16 v[8:11], v[156:159], v[214:217], v[8:11]
	v_mfma_f32_16x16x32_bf16 v[52:55], v[160:163], v[176:179], v[52:55]
	v_mfma_f32_16x16x32_bf16 v[48:51], v[168:171], v[176:179], v[48:51]
	v_mfma_f32_16x16x32_bf16 v[36:39], v[160:163], v[184:187], v[36:39]
	v_mfma_f32_16x16x32_bf16 v[32:35], v[168:171], v[184:187], v[32:35]
	v_mfma_f32_16x16x32_bf16 v[20:23], v[160:163], v[192:195], v[20:23]
	v_mfma_f32_16x16x32_bf16 v[16:19], v[168:171], v[192:195], v[16:19]
	v_mfma_f32_16x16x32_bf16 v[4:7], v[160:163], v[210:213], v[4:7]
	v_mfma_f32_16x16x32_bf16 v[0:3], v[168:171], v[210:213], v[0:3]
	v_mfma_f32_16x16x32_bf16 v[52:55], v[164:167], v[180:183], v[52:55]
	v_mfma_f32_16x16x32_bf16 v[48:51], v[172:175], v[180:183], v[48:51]
	v_mfma_f32_16x16x32_bf16 v[36:39], v[164:167], v[188:191], v[36:39]
	v_mfma_f32_16x16x32_bf16 v[32:35], v[172:175], v[188:191], v[32:35]
	v_mfma_f32_16x16x32_bf16 v[20:23], v[164:167], v[206:209], v[20:23]
	v_mfma_f32_16x16x32_bf16 v[16:19], v[172:175], v[206:209], v[16:19]
	v_mfma_f32_16x16x32_bf16 v[4:7], v[164:167], v[214:217], v[4:7]
	v_mfma_f32_16x16x32_bf16 v[0:3], v[172:175], v[214:217], v[0:3]
	s_setprio 0
	s_barrier
	s_add_i32 s72, 0, 0x18000
	s_add_i32 s75, 0, 0x1c000
	v_add_u32_e32 v156, s72, v145
	v_add_u32_e32 v172, s75, v145
	ds_read_b128 v[140:143], v156
	ds_read_b128 v[148:151], v156 offset:1024
	ds_read_b128 v[152:155], v156 offset:2048
	ds_read_b128 v[156:159], v156 offset:3072
	ds_read_b128 v[160:163], v172
	ds_read_b128 v[164:167], v172 offset:1024
	ds_read_b128 v[168:171], v172 offset:2048
	ds_read_b128 v[172:175], v172 offset:3072
	s_add_u32 s38, s38, 0x40000
	s_addc_u32 s39, s39, 0
	s_mov_b32 m0, s57
	v_lshl_add_u64 v[220:221], s[38:39], 0, v[130:131]
	ds_read_b128 v[176:179], v147 offset:32768
	ds_read_b128 v[180:183], v147 offset:33792
	ds_read_b128 v[184:187], v147 offset:34816
	ds_read_b128 v[188:191], v147 offset:35840
	ds_read_b128 v[192:195], v147 offset:36864
	ds_read_b128 v[206:209], v147 offset:37888
	ds_read_b128 v[210:213], v147 offset:38912
	ds_read_b128 v[214:217], v147 offset:39936
	global_load_lds_dwordx4 v[220:221], off
	v_lshl_add_u64 v[220:221], s[38:39], 0, v[132:133]
	s_mov_b32 m0, s62
	s_nop 0
	global_load_lds_dwordx4 v[220:221], off
	s_waitcnt vmcnt(8)
	s_waitcnt lgkmcnt(0)
	s_barrier
	s_setprio 1
	s_waitcnt lgkmcnt(0)
	v_mfma_f32_16x16x32_bf16 v[126:129], v[140:143], v[176:179], v[126:129]
	v_mfma_f32_16x16x32_bf16 v[122:125], v[152:155], v[176:179], v[122:125]
	v_mfma_f32_16x16x32_bf16 v[110:113], v[140:143], v[184:187], v[110:113]
	v_mfma_f32_16x16x32_bf16 v[106:109], v[152:155], v[184:187], v[106:109]
	v_mfma_f32_16x16x32_bf16 v[94:97], v[140:143], v[192:195], v[94:97]
	v_mfma_f32_16x16x32_bf16 v[90:93], v[152:155], v[192:195], v[90:93]
	v_mfma_f32_16x16x32_bf16 v[76:79], v[140:143], v[210:213], v[76:79]
	v_mfma_f32_16x16x32_bf16 v[72:75], v[152:155], v[210:213], v[72:75]
	v_mfma_f32_16x16x32_bf16 v[126:129], v[148:151], v[180:183], v[126:129]
	v_mfma_f32_16x16x32_bf16 v[122:125], v[156:159], v[180:183], v[122:125]
	v_mfma_f32_16x16x32_bf16 v[110:113], v[148:151], v[188:191], v[110:113]
	v_mfma_f32_16x16x32_bf16 v[106:109], v[156:159], v[188:191], v[106:109]
	v_mfma_f32_16x16x32_bf16 v[94:97], v[148:151], v[206:209], v[94:97]
	v_mfma_f32_16x16x32_bf16 v[90:93], v[156:159], v[206:209], v[90:93]
	v_mfma_f32_16x16x32_bf16 v[76:79], v[148:151], v[214:217], v[76:79]
	v_mfma_f32_16x16x32_bf16 v[72:75], v[156:159], v[214:217], v[72:75]
	v_mfma_f32_16x16x32_bf16 v[118:121], v[160:163], v[176:179], v[118:121]
	v_mfma_f32_16x16x32_bf16 v[114:117], v[168:171], v[176:179], v[114:117]
	v_mfma_f32_16x16x32_bf16 v[102:105], v[160:163], v[184:187], v[102:105]
	v_mfma_f32_16x16x32_bf16 v[98:101], v[168:171], v[184:187], v[98:101]
	v_mfma_f32_16x16x32_bf16 v[86:89], v[160:163], v[192:195], v[86:89]
	v_mfma_f32_16x16x32_bf16 v[82:85], v[168:171], v[192:195], v[82:85]
	v_mfma_f32_16x16x32_bf16 v[68:71], v[160:163], v[210:213], v[68:71]
	v_mfma_f32_16x16x32_bf16 v[64:67], v[168:171], v[210:213], v[64:67]
	v_mfma_f32_16x16x32_bf16 v[118:121], v[164:167], v[180:183], v[118:121]
	v_mfma_f32_16x16x32_bf16 v[114:117], v[172:175], v[180:183], v[114:117]
	v_mfma_f32_16x16x32_bf16 v[102:105], v[164:167], v[188:191], v[102:105]
	v_mfma_f32_16x16x32_bf16 v[98:101], v[172:175], v[188:191], v[98:101]
	v_mfma_f32_16x16x32_bf16 v[86:89], v[164:167], v[206:209], v[86:89]
	v_mfma_f32_16x16x32_bf16 v[82:85], v[172:175], v[206:209], v[82:85]
	v_mfma_f32_16x16x32_bf16 v[68:71], v[164:167], v[214:217], v[68:71]
	v_mfma_f32_16x16x32_bf16 v[64:67], v[172:175], v[214:217], v[64:67]
	s_setprio 0
	s_barrier
	s_add_i32 s38, s72, s55
	v_lshl_add_u64 v[198:199], v[198:199], 0, s[18:19]
	s_mov_b32 m0, s38
	ds_read_b128 v[176:179], v147 offset:49152
	ds_read_b128 v[180:183], v147 offset:50176
	ds_read_b128 v[184:187], v147 offset:51200
	ds_read_b128 v[188:191], v147 offset:52224
	ds_read_b128 v[192:195], v147 offset:53248
	ds_read_b128 v[206:209], v147 offset:54272
	ds_read_b128 v[210:213], v147 offset:55296
	ds_read_b128 v[214:217], v147 offset:56320
	global_load_lds_dwordx4 v[198:199], off
	s_add_i32 m0, s38, 0x2000
	s_add_u32 s24, s24, 0x40080
	v_lshl_add_u64 v[198:199], v[200:201], 0, s[18:19]
	s_addc_u32 s25, s25, 0
	s_add_i32 s38, s75, s55
	global_load_lds_dwordx4 v[198:199], off
	v_lshl_add_u64 v[198:199], s[24:25], 0, v[80:81]
	s_mov_b32 m0, s38
	s_nop 0
	global_load_lds_dwordx4 v[198:199], off
	v_lshl_add_u64 v[198:199], s[24:25], 0, v[134:135]
	s_add_i32 m0, s38, 0x2000
	s_nop 0
	global_load_lds_dwordx4 v[198:199], off
	v_lshl_add_u64 v[198:199], v[202:203], 0, s[18:19]
	s_mov_b32 m0, s63
	s_nop 0
	global_load_lds_dwordx4 v[198:199], off
	v_lshl_add_u64 v[198:199], v[218:219], 0, s[18:19]
	s_mov_b32 m0, s64
	s_nop 0
	global_load_lds_dwordx4 v[198:199], off
	s_waitcnt vmcnt(8)
	s_waitcnt lgkmcnt(0)
	s_barrier
	s_setprio 1
	s_waitcnt lgkmcnt(0)
	v_mfma_f32_16x16x32_bf16 v[60:63], v[140:143], v[176:179], v[60:63]
	v_mfma_f32_16x16x32_bf16 v[56:59], v[152:155], v[176:179], v[56:59]
	v_mfma_f32_16x16x32_bf16 v[44:47], v[140:143], v[184:187], v[44:47]
	v_mfma_f32_16x16x32_bf16 v[40:43], v[152:155], v[184:187], v[40:43]
	v_mfma_f32_16x16x32_bf16 v[28:31], v[140:143], v[192:195], v[28:31]
	v_mfma_f32_16x16x32_bf16 v[24:27], v[152:155], v[192:195], v[24:27]
	v_mfma_f32_16x16x32_bf16 v[12:15], v[140:143], v[210:213], v[12:15]
	v_mfma_f32_16x16x32_bf16 v[8:11], v[152:155], v[210:213], v[8:11]
	v_mfma_f32_16x16x32_bf16 v[60:63], v[148:151], v[180:183], v[60:63]
	v_mfma_f32_16x16x32_bf16 v[56:59], v[156:159], v[180:183], v[56:59]
	v_mfma_f32_16x16x32_bf16 v[44:47], v[148:151], v[188:191], v[44:47]
	v_mfma_f32_16x16x32_bf16 v[40:43], v[156:159], v[188:191], v[40:43]
	v_mfma_f32_16x16x32_bf16 v[28:31], v[148:151], v[206:209], v[28:31]
	v_mfma_f32_16x16x32_bf16 v[24:27], v[156:159], v[206:209], v[24:27]
	v_mfma_f32_16x16x32_bf16 v[12:15], v[148:151], v[214:217], v[12:15]
	v_mfma_f32_16x16x32_bf16 v[8:11], v[156:159], v[214:217], v[8:11]
	v_mfma_f32_16x16x32_bf16 v[52:55], v[160:163], v[176:179], v[52:55]
	v_mfma_f32_16x16x32_bf16 v[48:51], v[168:171], v[176:179], v[48:51]
	v_mfma_f32_16x16x32_bf16 v[36:39], v[160:163], v[184:187], v[36:39]
	v_mfma_f32_16x16x32_bf16 v[32:35], v[168:171], v[184:187], v[32:35]
	v_mfma_f32_16x16x32_bf16 v[20:23], v[160:163], v[192:195], v[20:23]
	v_mfma_f32_16x16x32_bf16 v[16:19], v[168:171], v[192:195], v[16:19]
	v_mfma_f32_16x16x32_bf16 v[4:7], v[160:163], v[210:213], v[4:7]
	v_mfma_f32_16x16x32_bf16 v[0:3], v[168:171], v[210:213], v[0:3]
	v_mfma_f32_16x16x32_bf16 v[52:55], v[164:167], v[180:183], v[52:55]
	v_mfma_f32_16x16x32_bf16 v[48:51], v[172:175], v[180:183], v[48:51]
	v_mfma_f32_16x16x32_bf16 v[36:39], v[164:167], v[188:191], v[36:39]
	v_mfma_f32_16x16x32_bf16 v[32:35], v[172:175], v[188:191], v[32:35]
	v_mfma_f32_16x16x32_bf16 v[20:23], v[164:167], v[206:209], v[20:23]
	v_mfma_f32_16x16x32_bf16 v[16:19], v[172:175], v[206:209], v[16:19]
	v_mfma_f32_16x16x32_bf16 v[4:7], v[164:167], v[214:217], v[4:7]
	v_mfma_f32_16x16x32_bf16 v[0:3], v[172:175], v[214:217], v[0:3]
	s_setprio 0
	s_barrier
	s_add_i32 s74, s74, 2
	s_add_u32 s68, s68, 0x100
	s_addc_u32 s69, s69, 0
	s_add_u32 s20, s20, 0x100
	s_addc_u32 s21, s21, 0
	s_cmp_gt_u32 s74, 13
	s_cbranch_scc0 .LBB0_338
	s_and_b64 vcc, exec, s[40:41]
	s_cbranch_vccz .LBB0_341
	s_barrier

.LBB0_411:
	s_add_u32 s36, s54, s78
	s_addc_u32 s37, s55, 0
	s_add_u32 s66, s36, 0x100
	s_addc_u32 s67, s37, 0
	s_and_b64 s[36:37], s[64:65], exec
	s_cselect_b32 s69, s47, s67
	s_cselect_b32 s68, s46, s66
	s_add_u32 s36, s52, s78
	s_addc_u32 s37, s53, 0
	s_add_u32 s66, s36, 0x100
	s_addc_u32 s67, s37, 0
	s_add_i32 s94, 0, 0x10000
	s_and_b64 s[36:37], s[64:65], exec
	v_add_u32_e32 v80, s94, v220
	s_cselect_b32 s67, s41, s67
	s_cselect_b32 s66, s72, s66
	s_add_i32 s95, 0, 0x14000
	ds_read_b128 v[156:159], v80
	ds_read_b128 v[160:163], v80 offset:1024
	ds_read_b128 v[164:167], v80 offset:2048
	ds_read_b128 v[168:171], v80 offset:3072
	v_add_u32_e32 v80, s95, v220
	ds_read_b128 v[140:143], v80
	ds_read_b128 v[144:147], v80 offset:1024
	ds_read_b128 v[148:151], v80 offset:2048
	ds_read_b128 v[152:155], v80 offset:3072
	s_add_u32 s36, s12, s78
	s_addc_u32 s37, s13, 0
	v_lshl_add_u64 v[82:83], s[36:37], 0, v[206:207]
	v_lshl_add_u64 v[82:83], v[82:83], 0, s[18:19]
	s_add_i32 m0, s51, 0xc000
	s_waitcnt lgkmcnt(0)
	ds_read_b128 v[172:175], v222
	ds_read_b128 v[176:179], v222 offset:1024
	ds_read_b128 v[180:183], v222 offset:2048
	ds_read_b128 v[184:187], v222 offset:3072
	ds_read_b128 v[188:191], v222 offset:4096
	ds_read_b128 v[192:195], v222 offset:5120
	ds_read_b128 v[198:201], v222 offset:6144
	ds_read_b128 v[214:217], v222 offset:7168
	global_load_lds_dwordx4 v[82:83], off
	v_lshl_add_u64 v[82:83], s[36:37], 0, v[210:211]
	v_lshl_add_u64 v[82:83], v[82:83], 0, s[18:19]
	s_add_i32 m0, s51, 0xe000
	s_nop 0
	global_load_lds_dwordx4 v[82:83], off
	s_waitcnt vmcnt(8)
	s_waitcnt lgkmcnt(0)
	s_barrier
	s_setprio 1
	s_waitcnt lgkmcnt(0)
	v_mfma_f32_16x16x32_bf16 v[124:127], v[156:159], v[172:175], v[136:139]
	v_mfma_f32_16x16x32_bf16 v[128:131], v[164:167], v[172:175], v[132:135]
	v_mfma_f32_16x16x32_bf16 v[120:123], v[156:159], v[180:183], v[120:123]
	v_mfma_f32_16x16x32_bf16 v[116:119], v[164:167], v[180:183], v[116:119]
	v_mfma_f32_16x16x32_bf16 v[112:115], v[156:159], v[188:191], v[112:115]
	v_mfma_f32_16x16x32_bf16 v[108:111], v[164:167], v[188:191], v[108:111]
	v_mfma_f32_16x16x32_bf16 v[104:107], v[156:159], v[198:201], v[104:107]
	v_mfma_f32_16x16x32_bf16 v[100:103], v[164:167], v[198:201], v[100:103]
	v_mfma_f32_16x16x32_bf16 v[124:127], v[160:163], v[176:179], v[124:127]
	v_mfma_f32_16x16x32_bf16 v[128:131], v[168:171], v[176:179], v[128:131]
	v_mfma_f32_16x16x32_bf16 v[120:123], v[160:163], v[184:187], v[120:123]
	v_mfma_f32_16x16x32_bf16 v[116:119], v[168:171], v[184:187], v[116:119]
	v_mfma_f32_16x16x32_bf16 v[112:115], v[160:163], v[192:195], v[112:115]
	v_mfma_f32_16x16x32_bf16 v[108:111], v[168:171], v[192:195], v[108:111]
	v_mfma_f32_16x16x32_bf16 v[104:107], v[160:163], v[214:217], v[104:107]
	v_mfma_f32_16x16x32_bf16 v[100:103], v[168:171], v[214:217], v[100:103]
	v_mfma_f32_16x16x32_bf16 v[76:79], v[140:143], v[172:175], v[76:79]
	v_mfma_f32_16x16x32_bf16 v[72:75], v[148:151], v[172:175], v[72:75]
	v_mfma_f32_16x16x32_bf16 v[60:63], v[140:143], v[180:183], v[60:63]
	v_mfma_f32_16x16x32_bf16 v[56:59], v[148:151], v[180:183], v[56:59]
	v_mfma_f32_16x16x32_bf16 v[44:47], v[140:143], v[188:191], v[44:47]
	v_mfma_f32_16x16x32_bf16 v[40:43], v[148:151], v[188:191], v[40:43]
	v_mfma_f32_16x16x32_bf16 v[36:39], v[140:143], v[198:201], v[36:39]
	v_mfma_f32_16x16x32_bf16 v[32:35], v[148:151], v[198:201], v[32:35]
	v_mfma_f32_16x16x32_bf16 v[76:79], v[144:147], v[176:179], v[76:79]
	v_mfma_f32_16x16x32_bf16 v[72:75], v[152:155], v[176:179], v[72:75]
	v_mfma_f32_16x16x32_bf16 v[60:63], v[144:147], v[184:187], v[60:63]
	v_mfma_f32_16x16x32_bf16 v[56:59], v[152:155], v[184:187], v[56:59]
	v_mfma_f32_16x16x32_bf16 v[44:47], v[144:147], v[192:195], v[44:47]
	v_mfma_f32_16x16x32_bf16 v[40:43], v[152:155], v[192:195], v[40:43]
	v_mfma_f32_16x16x32_bf16 v[36:39], v[144:147], v[214:217], v[36:39]
	v_mfma_f32_16x16x32_bf16 v[32:35], v[152:155], v[214:217], v[32:35]
	s_setprio 0
	s_barrier
	s_add_i32 s36, s94, s82
	v_lshl_add_u64 v[82:83], s[66:67], 0, v[208:209]
	s_mov_b32 m0, s36
	ds_read_b128 v[188:191], v222 offset:16384
	ds_read_b128 v[192:195], v222 offset:17408
	ds_read_b128 v[180:183], v222 offset:18432
	ds_read_b128 v[184:187], v222 offset:19456
	ds_read_b128 v[172:175], v222 offset:20480
	ds_read_b128 v[176:179], v222 offset:21504
	ds_read_b128 v[132:135], v222 offset:22528
	ds_read_b128 v[136:139], v222 offset:23552
	global_load_lds_dwordx4 v[82:83], off
	s_add_i32 m0, s36, 0x2000
	s_add_u32 s36, s66, 0x10000
	v_lshl_add_u64 v[214:215], s[66:67], 0, v[212:213]
	s_addc_u32 s37, s67, 0
	s_add_i32 s78, s95, s82
	global_load_lds_dwordx4 v[214:215], off
	v_lshl_add_u64 v[198:199], s[36:37], 0, v[208:209]
	s_mov_b32 m0, s78
	v_lshl_add_u64 v[216:217], s[68:69], 0, v[206:207]
	global_load_lds_dwordx4 v[198:199], off
	v_lshl_add_u64 v[198:199], s[36:37], 0, v[212:213]
	s_add_i32 m0, s78, 0x2000
	v_lshl_add_u64 v[218:219], s[68:69], 0, v[210:211]
	global_load_lds_dwordx4 v[198:199], off
	s_mov_b32 m0, s51
	v_cndmask_b32_e64 v80, 0, 1, s[56:57]
	global_load_lds_dwordx4 v[216:217], off
	s_mov_b32 m0, s83
	v_cmp_ne_u32_e64 s[36:37], 1, v80
	global_load_lds_dwordx4 v[218:219], off
	s_waitcnt vmcnt(8)
	s_waitcnt lgkmcnt(0)
	s_andn2_b64 vcc, exec, s[56:57]
	s_barrier
	s_cbranch_vccnz .LBB0_413
	s_setprio 1
	s_waitcnt lgkmcnt(0)
	v_mfma_f32_16x16x32_bf16 v[96:99], v[156:159], v[188:191], v[96:99]
	v_mfma_f32_16x16x32_bf16 v[92:95], v[164:167], v[188:191], v[92:95]
	v_mfma_f32_16x16x32_bf16 v[88:91], v[156:159], v[180:183], v[88:91]
	v_mfma_f32_16x16x32_bf16 v[84:87], v[164:167], v[180:183], v[84:87]
	v_mfma_f32_16x16x32_bf16 v[68:71], v[156:159], v[172:175], v[68:71]
	v_mfma_f32_16x16x32_bf16 v[64:67], v[164:167], v[172:175], v[64:67]
	v_mfma_f32_16x16x32_bf16 v[52:55], v[156:159], v[132:135], v[52:55]
	v_mfma_f32_16x16x32_bf16 v[48:51], v[164:167], v[132:135], v[48:51]
	v_mfma_f32_16x16x32_bf16 v[96:99], v[160:163], v[192:195], v[96:99]
	v_mfma_f32_16x16x32_bf16 v[92:95], v[168:171], v[192:195], v[92:95]
	v_mfma_f32_16x16x32_bf16 v[88:91], v[160:163], v[184:187], v[88:91]
	v_mfma_f32_16x16x32_bf16 v[84:87], v[168:171], v[184:187], v[84:87]
	v_mfma_f32_16x16x32_bf16 v[68:71], v[160:163], v[176:179], v[68:71]
	v_mfma_f32_16x16x32_bf16 v[64:67], v[168:171], v[176:179], v[64:67]
	v_mfma_f32_16x16x32_bf16 v[52:55], v[160:163], v[136:139], v[52:55]
	v_mfma_f32_16x16x32_bf16 v[48:51], v[168:171], v[136:139], v[48:51]
	v_mfma_f32_16x16x32_bf16 v[28:31], v[140:143], v[188:191], v[28:31]
	v_mfma_f32_16x16x32_bf16 v[24:27], v[148:151], v[188:191], v[24:27]
	v_mfma_f32_16x16x32_bf16 v[20:23], v[140:143], v[180:183], v[20:23]
	v_mfma_f32_16x16x32_bf16 v[16:19], v[148:151], v[180:183], v[16:19]
	v_mfma_f32_16x16x32_bf16 v[12:15], v[140:143], v[172:175], v[12:15]
	v_mfma_f32_16x16x32_bf16 v[8:11], v[148:151], v[172:175], v[8:11]
	v_mfma_f32_16x16x32_bf16 v[4:7], v[140:143], v[132:135], v[4:7]
	v_mfma_f32_16x16x32_bf16 v[0:3], v[148:151], v[132:135], v[0:3]
	v_mfma_f32_16x16x32_bf16 v[28:31], v[144:147], v[192:195], v[28:31]
	v_mfma_f32_16x16x32_bf16 v[24:27], v[152:155], v[192:195], v[24:27]
	v_mfma_f32_16x16x32_bf16 v[20:23], v[144:147], v[184:187], v[20:23]
	v_mfma_f32_16x16x32_bf16 v[16:19], v[152:155], v[184:187], v[16:19]
	v_mfma_f32_16x16x32_bf16 v[12:15], v[144:147], v[176:179], v[12:15]
	v_mfma_f32_16x16x32_bf16 v[8:11], v[152:155], v[176:179], v[8:11]
	v_mfma_f32_16x16x32_bf16 v[4:7], v[144:147], v[136:139], v[4:7]
	v_mfma_f32_16x16x32_bf16 v[0:3], v[152:155], v[136:139], v[0:3]
	s_setprio 0
.LBB0_413:
	s_barrier
	s_add_i32 s78, 0, 0x18000
	v_add_u32_e32 v80, s78, v220
	s_add_i32 s94, 0, 0x1c000
	ds_read_b128 v[156:159], v80
	ds_read_b128 v[160:163], v80 offset:1024
	ds_read_b128 v[164:167], v80 offset:2048
	ds_read_b128 v[168:171], v80 offset:3072
	v_add_u32_e32 v80, s94, v220
	ds_read_b128 v[140:143], v80
	ds_read_b128 v[144:147], v80 offset:1024
	ds_read_b128 v[148:151], v80 offset:2048
	ds_read_b128 v[152:155], v80 offset:3072
	s_and_b64 s[64:65], s[44:45], s[64:65]
	s_and_b64 s[64:65], s[64:65], exec
	s_cselect_b32 s64, s43, s39
	s_cselect_b32 s65, 0, 0
	s_add_u32 s64, s68, s64
	s_addc_u32 s65, s69, s65
	s_mov_b32 m0, s84
	s_waitcnt lgkmcnt(0)
	v_lshl_add_u64 v[132:133], s[64:65], 0, v[206:207]
	ds_read_b128 v[172:175], v222 offset:32768
	ds_read_b128 v[176:179], v222 offset:33792
	ds_read_b128 v[180:183], v222 offset:34816
	ds_read_b128 v[184:187], v222 offset:35840
	ds_read_b128 v[188:191], v222 offset:36864
	ds_read_b128 v[192:195], v222 offset:37888
	ds_read_b128 v[198:201], v222 offset:38912
	ds_read_b128 v[224:227], v222 offset:39936
	global_load_lds_dwordx4 v[132:133], off
	v_lshl_add_u64 v[132:133], s[64:65], 0, v[210:211]
	s_mov_b32 m0, s85
	s_nop 0
	global_load_lds_dwordx4 v[132:133], off
	s_waitcnt vmcnt(8)
	s_waitcnt lgkmcnt(0)
	s_barrier
	s_setprio 1
	s_waitcnt lgkmcnt(0)
	v_mfma_f32_16x16x32_bf16 v[124:127], v[156:159], v[172:175], v[124:127]
	v_mfma_f32_16x16x32_bf16 v[136:139], v[160:163], v[176:179], v[124:127]
	v_mfma_f32_16x16x32_bf16 v[124:127], v[164:167], v[172:175], v[128:131]
	v_mfma_f32_16x16x32_bf16 v[120:123], v[156:159], v[180:183], v[120:123]
	v_mfma_f32_16x16x32_bf16 v[116:119], v[164:167], v[180:183], v[116:119]
	v_mfma_f32_16x16x32_bf16 v[112:115], v[156:159], v[188:191], v[112:115]
	v_mfma_f32_16x16x32_bf16 v[108:111], v[164:167], v[188:191], v[108:111]
	v_mfma_f32_16x16x32_bf16 v[104:107], v[156:159], v[198:201], v[104:107]
	v_mfma_f32_16x16x32_bf16 v[100:103], v[164:167], v[198:201], v[100:103]
	v_mfma_f32_16x16x32_bf16 v[132:135], v[168:171], v[176:179], v[124:127]
	v_mfma_f32_16x16x32_bf16 v[120:123], v[160:163], v[184:187], v[120:123]
	v_mfma_f32_16x16x32_bf16 v[116:119], v[168:171], v[184:187], v[116:119]
	v_mfma_f32_16x16x32_bf16 v[112:115], v[160:163], v[192:195], v[112:115]
	v_mfma_f32_16x16x32_bf16 v[108:111], v[168:171], v[192:195], v[108:111]
	v_mfma_f32_16x16x32_bf16 v[104:107], v[160:163], v[224:227], v[104:107]
	v_mfma_f32_16x16x32_bf16 v[100:103], v[168:171], v[224:227], v[100:103]
	v_mfma_f32_16x16x32_bf16 v[76:79], v[140:143], v[172:175], v[76:79]
	v_mfma_f32_16x16x32_bf16 v[72:75], v[148:151], v[172:175], v[72:75]
	v_mfma_f32_16x16x32_bf16 v[60:63], v[140:143], v[180:183], v[60:63]
	v_mfma_f32_16x16x32_bf16 v[56:59], v[148:151], v[180:183], v[56:59]
	v_mfma_f32_16x16x32_bf16 v[44:47], v[140:143], v[188:191], v[44:47]
	v_mfma_f32_16x16x32_bf16 v[40:43], v[148:151], v[188:191], v[40:43]
	v_mfma_f32_16x16x32_bf16 v[36:39], v[140:143], v[198:201], v[36:39]
	v_mfma_f32_16x16x32_bf16 v[32:35], v[148:151], v[198:201], v[32:35]
	v_mfma_f32_16x16x32_bf16 v[76:79], v[144:147], v[176:179], v[76:79]
	v_mfma_f32_16x16x32_bf16 v[72:75], v[152:155], v[176:179], v[72:75]
	v_mfma_f32_16x16x32_bf16 v[60:63], v[144:147], v[184:187], v[60:63]
	v_mfma_f32_16x16x32_bf16 v[56:59], v[152:155], v[184:187], v[56:59]
	v_mfma_f32_16x16x32_bf16 v[44:47], v[144:147], v[192:195], v[44:47]
	v_mfma_f32_16x16x32_bf16 v[40:43], v[152:155], v[192:195], v[40:43]
	v_mfma_f32_16x16x32_bf16 v[36:39], v[144:147], v[224:227], v[36:39]
	v_mfma_f32_16x16x32_bf16 v[32:35], v[152:155], v[224:227], v[32:35]
	s_setprio 0
	s_barrier
	s_add_i32 s64, s78, s82
	v_lshl_add_u64 v[82:83], v[82:83], 0, s[18:19]
	s_mov_b32 m0, s64
	ds_read_b128 v[188:191], v222 offset:49152
	ds_read_b128 v[192:195], v222 offset:50176
	ds_read_b128 v[180:183], v222 offset:51200
	ds_read_b128 v[184:187], v222 offset:52224
	ds_read_b128 v[172:175], v222 offset:53248
	ds_read_b128 v[176:179], v222 offset:54272
	ds_read_b128 v[124:127], v222 offset:55296
	ds_read_b128 v[128:131], v222 offset:56320
	global_load_lds_dwordx4 v[82:83], off
	s_add_i32 m0, s64, 0x2000
	s_add_u32 s64, s66, 0x10080
	v_lshl_add_u64 v[82:83], v[214:215], 0, s[18:19]
	s_addc_u32 s65, s67, 0
	s_add_i32 s66, s94, s82
	global_load_lds_dwordx4 v[82:83], off
	v_lshl_add_u64 v[82:83], s[64:65], 0, v[208:209]
	s_mov_b32 m0, s66
	s_and_b64 vcc, exec, s[36:37]
	global_load_lds_dwordx4 v[82:83], off
	v_lshl_add_u64 v[82:83], s[64:65], 0, v[212:213]
	s_add_i32 m0, s66, 0x2000
	s_nop 0
	global_load_lds_dwordx4 v[82:83], off
	v_lshl_add_u64 v[82:83], v[216:217], 0, s[18:19]
	s_mov_b32 m0, s88
	s_nop 0
	global_load_lds_dwordx4 v[82:83], off
	v_lshl_add_u64 v[82:83], v[218:219], 0, s[18:19]
	s_mov_b32 m0, s89
	s_nop 0
	global_load_lds_dwordx4 v[82:83], off
	s_waitcnt vmcnt(8)
	s_waitcnt lgkmcnt(0)
	s_barrier
	s_cbranch_vccnz .LBB0_410
	s_setprio 1
	s_waitcnt lgkmcnt(0)
	v_mfma_f32_16x16x32_bf16 v[96:99], v[156:159], v[188:191], v[96:99]
	v_mfma_f32_16x16x32_bf16 v[92:95], v[164:167], v[188:191], v[92:95]
	v_mfma_f32_16x16x32_bf16 v[88:91], v[156:159], v[180:183], v[88:91]
	v_mfma_f32_16x16x32_bf16 v[82:85], v[164:167], v[180:183], v[84:87]
	v_mfma_f32_16x16x32_bf16 v[68:71], v[156:159], v[172:175], v[68:71]
	v_mfma_f32_16x16x32_bf16 v[64:67], v[164:167], v[172:175], v[64:67]
	v_mfma_f32_16x16x32_bf16 v[52:55], v[156:159], v[124:127], v[52:55]
	v_mfma_f32_16x16x32_bf16 v[48:51], v[164:167], v[124:127], v[48:51]
	v_mfma_f32_16x16x32_bf16 v[96:99], v[160:163], v[192:195], v[96:99]
	v_mfma_f32_16x16x32_bf16 v[92:95], v[168:171], v[192:195], v[92:95]
	v_mfma_f32_16x16x32_bf16 v[88:91], v[160:163], v[184:187], v[88:91]
	v_mfma_f32_16x16x32_bf16 v[84:87], v[168:171], v[184:187], v[82:85]
	v_mfma_f32_16x16x32_bf16 v[68:71], v[160:163], v[176:179], v[68:71]
	v_mfma_f32_16x16x32_bf16 v[64:67], v[168:171], v[176:179], v[64:67]
	v_mfma_f32_16x16x32_bf16 v[52:55], v[160:163], v[128:131], v[52:55]
	v_mfma_f32_16x16x32_bf16 v[48:51], v[168:171], v[128:131], v[48:51]
	v_mfma_f32_16x16x32_bf16 v[28:31], v[140:143], v[188:191], v[28:31]
	v_mfma_f32_16x16x32_bf16 v[24:27], v[148:151], v[188:191], v[24:27]
	v_mfma_f32_16x16x32_bf16 v[20:23], v[140:143], v[180:183], v[20:23]
	v_mfma_f32_16x16x32_bf16 v[16:19], v[148:151], v[180:183], v[16:19]
	v_mfma_f32_16x16x32_bf16 v[12:15], v[140:143], v[172:175], v[12:15]
	v_mfma_f32_16x16x32_bf16 v[8:11], v[148:151], v[172:175], v[8:11]
	v_mfma_f32_16x16x32_bf16 v[4:7], v[140:143], v[124:127], v[4:7]
	v_mfma_f32_16x16x32_bf16 v[0:3], v[148:151], v[124:127], v[0:3]
	v_mfma_f32_16x16x32_bf16 v[28:31], v[144:147], v[192:195], v[28:31]
	v_mfma_f32_16x16x32_bf16 v[24:27], v[152:155], v[192:195], v[24:27]
	v_mfma_f32_16x16x32_bf16 v[20:23], v[144:147], v[184:187], v[20:23]
	v_mfma_f32_16x16x32_bf16 v[16:19], v[152:155], v[184:187], v[16:19]
	v_mfma_f32_16x16x32_bf16 v[12:15], v[144:147], v[176:179], v[12:15]
	v_mfma_f32_16x16x32_bf16 v[8:11], v[152:155], v[176:179], v[8:11]
	v_mfma_f32_16x16x32_bf16 v[4:7], v[144:147], v[128:131], v[4:7]
	v_mfma_f32_16x16x32_bf16 v[0:3], v[152:155], v[128:131], v[0:3]
	s_setprio 0
	s_branch .LBB0_410

.LBB0_607:
	s_add_u32 s36, s50, s52
	s_addc_u32 s37, s51, s53
	s_add_u32 s56, s36, 0x10000
	s_addc_u32 s57, s37, 0
	s_add_u32 s66, s91, s52
	s_addc_u32 s67, s96, s53
	s_add_i32 s94, 0, 0x10000
	s_cmp_eq_u32 s52, 0x1f0000
	s_cselect_b64 s[64:65], -1, 0
	s_and_b64 s[36:37], s[64:65], exec
	s_cselect_b32 s63, s39, s57
	s_cselect_b32 s62, s88, s56
	v_add_u32_e32 v80, s94, v220
	s_cselect_b32 s57, s25, s67
	s_cselect_b32 s56, s90, s66
	s_add_i32 s66, 0, 0x14000
	ds_read_b128 v[154:157], v80
	ds_read_b128 v[158:161], v80 offset:1024
	ds_read_b128 v[162:165], v80 offset:2048
	ds_read_b128 v[166:169], v80 offset:3072
	v_add_u32_e32 v80, s66, v220
	ds_read_b128 v[130:133], v80
	ds_read_b128 v[142:145], v80 offset:1024
	ds_read_b128 v[146:149], v80 offset:2048
	ds_read_b128 v[150:153], v80 offset:3072
	s_waitcnt lgkmcnt(0)
	v_lshl_add_u64 v[114:115], v[218:219], 0, s[52:53]
	s_add_i32 m0, s47, 0xc000
	ds_read_b128 v[170:173], v222
	ds_read_b128 v[174:177], v222 offset:1024
	ds_read_b128 v[178:181], v222 offset:2048
	ds_read_b128 v[182:185], v222 offset:3072
	ds_read_b128 v[186:189], v222 offset:4096
	ds_read_b128 v[190:193], v222 offset:5120
	ds_read_b128 v[224:227], v222 offset:6144
	ds_read_b128 v[240:243], v222 offset:7168
	global_load_lds_dwordx4 v[114:115], off
	v_lshl_add_u64 v[114:115], v[216:217], 0, s[52:53]
	s_add_i32 m0, s47, 0xe000
	s_nop 0
	global_load_lds_dwordx4 v[114:115], off
	s_waitcnt vmcnt(8)
	s_waitcnt lgkmcnt(0)
	s_barrier
	s_setprio 1
	s_waitcnt lgkmcnt(0)
	v_mfma_f32_16x16x32_bf16 v[114:117], v[154:157], v[170:173], v[138:141]
	v_mfma_f32_16x16x32_bf16 v[126:129], v[162:165], v[170:173], v[134:137]
	v_mfma_f32_16x16x32_bf16 v[122:125], v[154:157], v[178:181], v[122:125]
	v_mfma_f32_16x16x32_bf16 v[118:121], v[162:165], v[178:181], v[118:121]
	v_mfma_f32_16x16x32_bf16 v[110:113], v[154:157], v[186:189], v[110:113]
	v_mfma_f32_16x16x32_bf16 v[106:109], v[162:165], v[186:189], v[106:109]
	v_mfma_f32_16x16x32_bf16 v[102:105], v[154:157], v[224:227], v[102:105]
	v_mfma_f32_16x16x32_bf16 v[98:101], v[162:165], v[224:227], v[98:101]
	v_mfma_f32_16x16x32_bf16 v[114:117], v[158:161], v[174:177], v[114:117]
	v_mfma_f32_16x16x32_bf16 v[126:129], v[166:169], v[174:177], v[126:129]
	v_mfma_f32_16x16x32_bf16 v[122:125], v[158:161], v[182:185], v[122:125]
	v_mfma_f32_16x16x32_bf16 v[118:121], v[166:169], v[182:185], v[118:121]
	v_mfma_f32_16x16x32_bf16 v[110:113], v[158:161], v[190:193], v[110:113]
	v_mfma_f32_16x16x32_bf16 v[106:109], v[166:169], v[190:193], v[106:109]
	v_mfma_f32_16x16x32_bf16 v[102:105], v[158:161], v[240:243], v[102:105]
	v_mfma_f32_16x16x32_bf16 v[98:101], v[166:169], v[240:243], v[98:101]
	v_mfma_f32_16x16x32_bf16 v[86:89], v[130:133], v[170:173], v[86:89]
	v_mfma_f32_16x16x32_bf16 v[82:85], v[146:149], v[170:173], v[82:85]
	v_mfma_f32_16x16x32_bf16 v[68:71], v[130:133], v[178:181], v[68:71]
	v_mfma_f32_16x16x32_bf16 v[64:67], v[146:149], v[178:181], v[64:67]
	v_mfma_f32_16x16x32_bf16 v[52:55], v[130:133], v[186:189], v[52:55]
	v_mfma_f32_16x16x32_bf16 v[48:51], v[146:149], v[186:189], v[48:51]
	v_mfma_f32_16x16x32_bf16 v[36:39], v[130:133], v[224:227], v[36:39]
	v_mfma_f32_16x16x32_bf16 v[32:35], v[146:149], v[224:227], v[32:35]
	v_mfma_f32_16x16x32_bf16 v[86:89], v[142:145], v[174:177], v[86:89]
	v_mfma_f32_16x16x32_bf16 v[82:85], v[150:153], v[174:177], v[82:85]
	v_mfma_f32_16x16x32_bf16 v[68:71], v[142:145], v[182:185], v[68:71]
	v_mfma_f32_16x16x32_bf16 v[64:67], v[150:153], v[182:185], v[64:67]
	v_mfma_f32_16x16x32_bf16 v[52:55], v[142:145], v[190:193], v[52:55]
	v_mfma_f32_16x16x32_bf16 v[48:51], v[150:153], v[190:193], v[48:51]
	v_mfma_f32_16x16x32_bf16 v[36:39], v[142:145], v[240:243], v[36:39]
	v_mfma_f32_16x16x32_bf16 v[32:35], v[150:153], v[240:243], v[32:35]
	s_setprio 0
	s_barrier
	s_add_i32 s36, s94, s78
	v_lshl_add_u64 v[198:199], s[56:57], 0, v[206:207]
	s_mov_b32 m0, s36
	ds_read_b128 v[186:189], v222 offset:16384
	ds_read_b128 v[190:193], v222 offset:17408
	ds_read_b128 v[178:181], v222 offset:18432
	ds_read_b128 v[182:185], v222 offset:19456
	ds_read_b128 v[170:173], v222 offset:20480
	ds_read_b128 v[174:177], v222 offset:21504
	ds_read_b128 v[134:137], v222 offset:22528
	ds_read_b128 v[138:141], v222 offset:23552
	global_load_lds_dwordx4 v[198:199], off
	s_add_i32 m0, s36, 0x2000
	s_add_u32 s36, s56, 0x4000
	v_lshl_add_u64 v[198:199], s[56:57], 0, v[210:211]
	s_addc_u32 s37, s57, 0
	s_add_i32 s66, s66, s78
	global_load_lds_dwordx4 v[198:199], off
	v_lshl_add_u64 v[198:199], s[36:37], 0, v[206:207]
	s_mov_b32 m0, s66
	v_cndmask_b32_e64 v80, 0, 1, s[54:55]
	global_load_lds_dwordx4 v[198:199], off
	v_lshl_add_u64 v[198:199], s[36:37], 0, v[210:211]
	s_add_i32 m0, s66, 0x2000
	v_cmp_ne_u32_e64 s[36:37], 1, v80
	global_load_lds_dwordx4 v[198:199], off
	v_lshl_add_u64 v[198:199], s[62:63], 0, v[194:195]
	s_mov_b32 m0, s47
	s_andn2_b64 vcc, exec, s[54:55]
	global_load_lds_dwordx4 v[198:199], off
	v_lshl_add_u64 v[198:199], s[62:63], 0, v[208:209]
	s_mov_b32 m0, s49
	s_nop 0
	global_load_lds_dwordx4 v[198:199], off
	s_waitcnt vmcnt(8)
	s_waitcnt lgkmcnt(0)
	s_barrier
	s_cbranch_vccnz .LBB0_609
	s_setprio 1
	s_waitcnt lgkmcnt(0)
	v_mfma_f32_16x16x32_bf16 v[94:97], v[154:157], v[186:189], v[94:97]
	v_mfma_f32_16x16x32_bf16 v[90:93], v[162:165], v[186:189], v[90:93]
	v_mfma_f32_16x16x32_bf16 v[76:79], v[154:157], v[178:181], v[76:79]
	v_mfma_f32_16x16x32_bf16 v[72:75], v[162:165], v[178:181], v[72:75]
	v_mfma_f32_16x16x32_bf16 v[60:63], v[154:157], v[170:173], v[60:63]
	v_mfma_f32_16x16x32_bf16 v[56:59], v[162:165], v[170:173], v[56:59]
	v_mfma_f32_16x16x32_bf16 v[44:47], v[154:157], v[134:137], v[44:47]
	v_mfma_f32_16x16x32_bf16 v[40:43], v[162:165], v[134:137], v[40:43]
	v_mfma_f32_16x16x32_bf16 v[94:97], v[158:161], v[190:193], v[94:97]
	v_mfma_f32_16x16x32_bf16 v[90:93], v[166:169], v[190:193], v[90:93]
	v_mfma_f32_16x16x32_bf16 v[76:79], v[158:161], v[182:185], v[76:79]
	v_mfma_f32_16x16x32_bf16 v[72:75], v[166:169], v[182:185], v[72:75]
	v_mfma_f32_16x16x32_bf16 v[60:63], v[158:161], v[174:177], v[60:63]
	v_mfma_f32_16x16x32_bf16 v[56:59], v[166:169], v[174:177], v[56:59]
	v_mfma_f32_16x16x32_bf16 v[44:47], v[158:161], v[138:141], v[44:47]
	v_mfma_f32_16x16x32_bf16 v[40:43], v[166:169], v[138:141], v[40:43]
	v_mfma_f32_16x16x32_bf16 v[28:31], v[130:133], v[186:189], v[28:31]
	v_mfma_f32_16x16x32_bf16 v[24:27], v[146:149], v[186:189], v[24:27]
	v_mfma_f32_16x16x32_bf16 v[20:23], v[130:133], v[178:181], v[20:23]
	v_mfma_f32_16x16x32_bf16 v[16:19], v[146:149], v[178:181], v[16:19]
	v_mfma_f32_16x16x32_bf16 v[12:15], v[130:133], v[170:173], v[12:15]
	v_mfma_f32_16x16x32_bf16 v[8:11], v[146:149], v[170:173], v[8:11]
	v_mfma_f32_16x16x32_bf16 v[4:7], v[130:133], v[134:137], v[4:7]
	v_mfma_f32_16x16x32_bf16 v[0:3], v[146:149], v[134:137], v[0:3]
	v_mfma_f32_16x16x32_bf16 v[28:31], v[142:145], v[190:193], v[28:31]
	v_mfma_f32_16x16x32_bf16 v[24:27], v[150:153], v[190:193], v[24:27]
	v_mfma_f32_16x16x32_bf16 v[20:23], v[142:145], v[182:185], v[20:23]
	v_mfma_f32_16x16x32_bf16 v[16:19], v[150:153], v[182:185], v[16:19]
	v_mfma_f32_16x16x32_bf16 v[12:15], v[142:145], v[174:177], v[12:15]
	v_mfma_f32_16x16x32_bf16 v[8:11], v[150:153], v[174:177], v[8:11]
	v_mfma_f32_16x16x32_bf16 v[4:7], v[142:145], v[138:141], v[4:7]
	v_mfma_f32_16x16x32_bf16 v[0:3], v[150:153], v[138:141], v[0:3]
	s_setprio 0
.LBB0_609:
	s_add_u32 s66, s62, 0x8000
	s_addc_u32 s67, s63, 0
	s_add_u32 s94, s56, 0x8000
	s_addc_u32 s95, s57, 0
	s_barrier
	s_add_i32 vcc_lo, 0, 0x18000
	v_add_u32_e32 v80, vcc_lo, v220
	s_add_i32 vcc_hi, 0, 0x1c000
	ds_read_b128 v[154:157], v80
	ds_read_b128 v[158:161], v80 offset:1024
	ds_read_b128 v[162:165], v80 offset:2048
	ds_read_b128 v[166:169], v80 offset:3072
	v_add_u32_e32 v80, vcc_hi, v220
	ds_read_b128 v[130:133], v80
	ds_read_b128 v[142:145], v80 offset:1024
	ds_read_b128 v[146:149], v80 offset:2048
	ds_read_b128 v[150:153], v80 offset:3072
	s_and_b64 s[64:65], s[42:43], s[64:65]
	s_and_b64 s[64:65], s[64:65], exec
	s_cselect_b32 s65, s89, s10
	s_cselect_b32 s64, 0, 0
	s_add_u32 s62, s62, s65
	s_addc_u32 s63, s63, s64
	s_mov_b32 m0, s79
	s_waitcnt lgkmcnt(0)
	v_lshl_add_u64 v[134:135], s[62:63], 0, v[194:195]
	ds_read_b128 v[170:173], v222 offset:32768
	ds_read_b128 v[174:177], v222 offset:33792
	ds_read_b128 v[178:181], v222 offset:34816
	ds_read_b128 v[182:185], v222 offset:35840
	ds_read_b128 v[186:189], v222 offset:36864
	ds_read_b128 v[190:193], v222 offset:37888
	ds_read_b128 v[224:227], v222 offset:38912
	ds_read_b128 v[240:243], v222 offset:39936
	global_load_lds_dwordx4 v[134:135], off
	v_lshl_add_u64 v[134:135], s[62:63], 0, v[208:209]
	s_mov_b32 m0, s80
	s_nop 0
	global_load_lds_dwordx4 v[134:135], off
	s_waitcnt vmcnt(8)
	s_waitcnt lgkmcnt(0)
	s_barrier
	s_setprio 1
	s_waitcnt lgkmcnt(0)
	v_mfma_f32_16x16x32_bf16 v[114:117], v[154:157], v[170:173], v[114:117]
	v_mfma_f32_16x16x32_bf16 v[138:141], v[158:161], v[174:177], v[114:117]
	v_mfma_f32_16x16x32_bf16 v[114:117], v[162:165], v[170:173], v[126:129]
	v_mfma_f32_16x16x32_bf16 v[134:137], v[166:169], v[174:177], v[114:117]
	v_mfma_f32_16x16x32_bf16 v[114:117], v[154:157], v[178:181], v[122:125]
	v_mfma_f32_16x16x32_bf16 v[122:125], v[158:161], v[182:185], v[114:117]
	v_mfma_f32_16x16x32_bf16 v[114:117], v[162:165], v[178:181], v[118:121]
	v_mfma_f32_16x16x32_bf16 v[110:113], v[154:157], v[186:189], v[110:113]
	v_mfma_f32_16x16x32_bf16 v[106:109], v[162:165], v[186:189], v[106:109]
	v_mfma_f32_16x16x32_bf16 v[102:105], v[154:157], v[224:227], v[102:105]
	v_mfma_f32_16x16x32_bf16 v[98:101], v[162:165], v[224:227], v[98:101]
	v_mfma_f32_16x16x32_bf16 v[118:121], v[166:169], v[182:185], v[114:117]
	v_mfma_f32_16x16x32_bf16 v[110:113], v[158:161], v[190:193], v[110:113]
	v_mfma_f32_16x16x32_bf16 v[106:109], v[166:169], v[190:193], v[106:109]
	v_mfma_f32_16x16x32_bf16 v[102:105], v[158:161], v[240:243], v[102:105]
	v_mfma_f32_16x16x32_bf16 v[98:101], v[166:169], v[240:243], v[98:101]
	v_mfma_f32_16x16x32_bf16 v[86:89], v[130:133], v[170:173], v[86:89]
	v_mfma_f32_16x16x32_bf16 v[82:85], v[146:149], v[170:173], v[82:85]
	v_mfma_f32_16x16x32_bf16 v[68:71], v[130:133], v[178:181], v[68:71]
	v_mfma_f32_16x16x32_bf16 v[64:67], v[146:149], v[178:181], v[64:67]
	v_mfma_f32_16x16x32_bf16 v[52:55], v[130:133], v[186:189], v[52:55]
	v_mfma_f32_16x16x32_bf16 v[48:51], v[146:149], v[186:189], v[48:51]
	v_mfma_f32_16x16x32_bf16 v[36:39], v[130:133], v[224:227], v[36:39]
	v_mfma_f32_16x16x32_bf16 v[32:35], v[146:149], v[224:227], v[32:35]
	v_mfma_f32_16x16x32_bf16 v[86:89], v[142:145], v[174:177], v[86:89]
	v_mfma_f32_16x16x32_bf16 v[82:85], v[150:153], v[174:177], v[82:85]
	v_mfma_f32_16x16x32_bf16 v[68:71], v[142:145], v[182:185], v[68:71]
	v_mfma_f32_16x16x32_bf16 v[64:67], v[150:153], v[182:185], v[64:67]
	v_mfma_f32_16x16x32_bf16 v[52:55], v[142:145], v[190:193], v[52:55]
	v_mfma_f32_16x16x32_bf16 v[48:51], v[150:153], v[190:193], v[48:51]
	v_mfma_f32_16x16x32_bf16 v[36:39], v[142:145], v[240:243], v[36:39]
	v_mfma_f32_16x16x32_bf16 v[32:35], v[150:153], v[240:243], v[32:35]
	s_setprio 0
	s_barrier
	s_add_i32 s62, vcc_lo, s78
	v_lshl_add_u64 v[198:199], s[94:95], 0, v[206:207]
	s_mov_b32 m0, s62
	ds_read_b128 v[186:189], v222 offset:49152
	ds_read_b128 v[190:193], v222 offset:50176
	ds_read_b128 v[178:181], v222 offset:51200
	ds_read_b128 v[182:185], v222 offset:52224
	ds_read_b128 v[170:173], v222 offset:53248
	ds_read_b128 v[174:177], v222 offset:54272
	ds_read_b128 v[114:117], v222 offset:55296
	ds_read_b128 v[126:129], v222 offset:56320
	global_load_lds_dwordx4 v[198:199], off
	s_add_i32 m0, s62, 0x2000
	s_add_u32 s56, s56, 0xc000
	v_lshl_add_u64 v[198:199], s[94:95], 0, v[210:211]
	s_addc_u32 s57, s57, 0
	s_add_i32 s62, vcc_hi, s78
	global_load_lds_dwordx4 v[198:199], off
	v_lshl_add_u64 v[198:199], s[56:57], 0, v[206:207]
	s_mov_b32 m0, s62
	s_and_b64 vcc, exec, s[36:37]
	global_load_lds_dwordx4 v[198:199], off
	v_lshl_add_u64 v[198:199], s[56:57], 0, v[210:211]
	s_add_i32 m0, s62, 0x2000
	s_nop 0
	global_load_lds_dwordx4 v[198:199], off
	v_lshl_add_u64 v[198:199], s[66:67], 0, v[194:195]
	s_mov_b32 m0, s81
	s_nop 0
	global_load_lds_dwordx4 v[198:199], off
	v_lshl_add_u64 v[198:199], s[66:67], 0, v[208:209]
	s_mov_b32 m0, s82
	s_nop 0
	global_load_lds_dwordx4 v[198:199], off
	s_waitcnt vmcnt(8)
	s_waitcnt lgkmcnt(0)
	s_barrier
	s_cbranch_vccnz .LBB0_606
	s_setprio 1
	s_waitcnt lgkmcnt(0)
	v_mfma_f32_16x16x32_bf16 v[94:97], v[154:157], v[186:189], v[94:97]
	v_mfma_f32_16x16x32_bf16 v[90:93], v[162:165], v[186:189], v[90:93]
	v_mfma_f32_16x16x32_bf16 v[76:79], v[154:157], v[178:181], v[76:79]
	v_mfma_f32_16x16x32_bf16 v[72:75], v[162:165], v[178:181], v[72:75]
	v_mfma_f32_16x16x32_bf16 v[60:63], v[154:157], v[170:173], v[60:63]
	v_mfma_f32_16x16x32_bf16 v[56:59], v[162:165], v[170:173], v[56:59]
	v_mfma_f32_16x16x32_bf16 v[44:47], v[154:157], v[114:117], v[44:47]
	v_mfma_f32_16x16x32_bf16 v[40:43], v[162:165], v[114:117], v[40:43]
	v_mfma_f32_16x16x32_bf16 v[94:97], v[158:161], v[190:193], v[94:97]
	v_mfma_f32_16x16x32_bf16 v[90:93], v[166:169], v[190:193], v[90:93]
	v_mfma_f32_16x16x32_bf16 v[76:79], v[158:161], v[182:185], v[76:79]
	v_mfma_f32_16x16x32_bf16 v[72:75], v[166:169], v[182:185], v[72:75]
	v_mfma_f32_16x16x32_bf16 v[60:63], v[158:161], v[174:177], v[60:63]
	v_mfma_f32_16x16x32_bf16 v[56:59], v[166:169], v[174:177], v[56:59]
	v_mfma_f32_16x16x32_bf16 v[44:47], v[158:161], v[126:129], v[44:47]
	v_mfma_f32_16x16x32_bf16 v[40:43], v[166:169], v[126:129], v[40:43]
	v_mfma_f32_16x16x32_bf16 v[28:31], v[130:133], v[186:189], v[28:31]
	v_mfma_f32_16x16x32_bf16 v[24:27], v[146:149], v[186:189], v[24:27]
	v_mfma_f32_16x16x32_bf16 v[20:23], v[130:133], v[178:181], v[20:23]
	v_mfma_f32_16x16x32_bf16 v[16:19], v[146:149], v[178:181], v[16:19]
	v_mfma_f32_16x16x32_bf16 v[12:15], v[130:133], v[170:173], v[12:15]
	v_mfma_f32_16x16x32_bf16 v[8:11], v[146:149], v[170:173], v[8:11]
	v_mfma_f32_16x16x32_bf16 v[4:7], v[130:133], v[114:117], v[4:7]
	v_mfma_f32_16x16x32_bf16 v[0:3], v[146:149], v[114:117], v[0:3]
	v_mfma_f32_16x16x32_bf16 v[28:31], v[142:145], v[190:193], v[28:31]
	v_mfma_f32_16x16x32_bf16 v[24:27], v[150:153], v[190:193], v[24:27]
	v_mfma_f32_16x16x32_bf16 v[20:23], v[142:145], v[182:185], v[20:23]
	v_mfma_f32_16x16x32_bf16 v[16:19], v[150:153], v[182:185], v[16:19]
	v_mfma_f32_16x16x32_bf16 v[12:15], v[142:145], v[174:177], v[12:15]
	v_mfma_f32_16x16x32_bf16 v[8:11], v[150:153], v[174:177], v[8:11]
	v_mfma_f32_16x16x32_bf16 v[4:7], v[142:145], v[126:129], v[4:7]
	v_mfma_f32_16x16x32_bf16 v[0:3], v[150:153], v[126:129], v[0:3]
	s_setprio 0
	s_branch .LBB0_606

.LBB0_651:
	s_add_u32 s40, s38, 0xfffc0080
	s_addc_u32 s41, s39, -1
	s_add_i32 s73, 0, 0x10000
	s_cmp_eq_u32 s72, 12
	s_cselect_b32 s43, s9, s41
	s_cselect_b32 s42, s25, s40
	s_cselect_b32 s41, s7, s69
	s_cselect_b32 s40, s67, s68
	s_add_i32 s76, 0, 0x14000
	v_add_u32_e32 v172, s73, v158
	v_add_u32_e32 v188, s76, v158
	ds_read_b128 v[160:163], v172
	ds_read_b128 v[164:167], v172 offset:1024
	ds_read_b128 v[168:171], v172 offset:2048
	ds_read_b128 v[172:175], v172 offset:3072
	ds_read_b128 v[176:179], v188
	ds_read_b128 v[180:183], v188 offset:1024
	ds_read_b128 v[184:187], v188 offset:2048
	ds_read_b128 v[188:191], v188 offset:3072
	v_lshl_add_u64 v[198:199], s[38:39], 0, v[156:157]
	s_add_i32 m0, s51, 0xc000
	ds_read_b128 v[192:195], v159
	ds_read_b128 v[206:209], v159 offset:1024
	ds_read_b128 v[210:213], v159 offset:2048
	ds_read_b128 v[214:217], v159 offset:3072
	ds_read_b128 v[218:221], v159 offset:4096
	ds_read_b128 v[222:225], v159 offset:5120
	ds_read_b128 v[240:243], v159 offset:6144
	ds_read_b128 v[244:247], v159 offset:7168
	global_load_lds_dwordx4 v[198:199], off
	v_lshl_add_u64 v[198:199], s[38:39], 0, v[154:155]
	s_add_i32 m0, s51, 0xe000
	s_nop 0
	global_load_lds_dwordx4 v[198:199], off
	s_waitcnt vmcnt(8)
	s_waitcnt lgkmcnt(0)
	s_barrier
	s_setprio 1
	s_waitcnt lgkmcnt(0)
	v_mfma_f32_16x16x32_bf16 v[126:129], v[160:163], v[192:195], v[126:129]
	v_mfma_f32_16x16x32_bf16 v[122:125], v[168:171], v[192:195], v[122:125]
	v_mfma_f32_16x16x32_bf16 v[110:113], v[160:163], v[210:213], v[110:113]
	v_mfma_f32_16x16x32_bf16 v[106:109], v[168:171], v[210:213], v[106:109]
	v_mfma_f32_16x16x32_bf16 v[94:97], v[160:163], v[218:221], v[94:97]
	v_mfma_f32_16x16x32_bf16 v[90:93], v[168:171], v[218:221], v[90:93]
	v_mfma_f32_16x16x32_bf16 v[76:79], v[160:163], v[240:243], v[76:79]
	v_mfma_f32_16x16x32_bf16 v[72:75], v[168:171], v[240:243], v[72:75]
	v_mfma_f32_16x16x32_bf16 v[126:129], v[164:167], v[206:209], v[126:129]
	v_mfma_f32_16x16x32_bf16 v[122:125], v[172:175], v[206:209], v[122:125]
	v_mfma_f32_16x16x32_bf16 v[110:113], v[164:167], v[214:217], v[110:113]
	v_mfma_f32_16x16x32_bf16 v[106:109], v[172:175], v[214:217], v[106:109]
	v_mfma_f32_16x16x32_bf16 v[94:97], v[164:167], v[222:225], v[94:97]
	v_mfma_f32_16x16x32_bf16 v[90:93], v[172:175], v[222:225], v[90:93]
	v_mfma_f32_16x16x32_bf16 v[76:79], v[164:167], v[244:247], v[76:79]
	v_mfma_f32_16x16x32_bf16 v[72:75], v[172:175], v[244:247], v[72:75]
	v_mfma_f32_16x16x32_bf16 v[118:121], v[176:179], v[192:195], v[118:121]
	v_mfma_f32_16x16x32_bf16 v[114:117], v[184:187], v[192:195], v[114:117]
	v_mfma_f32_16x16x32_bf16 v[102:105], v[176:179], v[210:213], v[102:105]
	v_mfma_f32_16x16x32_bf16 v[98:101], v[184:187], v[210:213], v[98:101]
	v_mfma_f32_16x16x32_bf16 v[86:89], v[176:179], v[218:221], v[86:89]
	v_mfma_f32_16x16x32_bf16 v[82:85], v[184:187], v[218:221], v[82:85]
	v_mfma_f32_16x16x32_bf16 v[68:71], v[176:179], v[240:243], v[68:71]
	v_mfma_f32_16x16x32_bf16 v[64:67], v[184:187], v[240:243], v[64:67]
	v_mfma_f32_16x16x32_bf16 v[118:121], v[180:183], v[206:209], v[118:121]
	v_mfma_f32_16x16x32_bf16 v[114:117], v[188:191], v[206:209], v[114:117]
	v_mfma_f32_16x16x32_bf16 v[102:105], v[180:183], v[214:217], v[102:105]
	v_mfma_f32_16x16x32_bf16 v[98:101], v[188:191], v[214:217], v[98:101]
	v_mfma_f32_16x16x32_bf16 v[86:89], v[180:183], v[222:225], v[86:89]
	v_mfma_f32_16x16x32_bf16 v[82:85], v[188:191], v[222:225], v[82:85]
	v_mfma_f32_16x16x32_bf16 v[68:71], v[180:183], v[244:247], v[68:71]
	v_mfma_f32_16x16x32_bf16 v[64:67], v[188:191], v[244:247], v[64:67]
	s_setprio 0
	s_barrier
	s_add_i32 s73, s73, s49
	v_lshl_add_u64 v[198:199], s[40:41], 0, v[134:135]
	s_mov_b32 m0, s73
	ds_read_b128 v[192:195], v159 offset:16384
	ds_read_b128 v[206:209], v159 offset:17408
	ds_read_b128 v[210:213], v159 offset:18432
	ds_read_b128 v[214:217], v159 offset:19456
	ds_read_b128 v[218:221], v159 offset:20480
	ds_read_b128 v[222:225], v159 offset:21504
	ds_read_b128 v[240:243], v159 offset:22528
	ds_read_b128 v[244:247], v159 offset:23552
	global_load_lds_dwordx4 v[198:199], off
	s_add_i32 m0, s73, 0x2000
	s_add_u32 s74, s40, 0x40000
	v_lshl_add_u64 v[200:201], s[40:41], 0, v[130:131]
	s_addc_u32 s75, s41, 0
	s_add_i32 s73, s76, s49
	global_load_lds_dwordx4 v[200:201], off
	v_lshl_add_u64 v[202:203], s[74:75], 0, v[134:135]
	s_mov_b32 m0, s73
	v_lshl_add_u64 v[226:227], s[42:43], 0, v[132:133]
	global_load_lds_dwordx4 v[202:203], off
	v_lshl_add_u64 v[202:203], s[74:75], 0, v[130:131]
	s_add_i32 m0, s73, 0x2000
	s_nop 0
	global_load_lds_dwordx4 v[202:203], off
	v_lshl_add_u64 v[202:203], s[42:43], 0, v[136:137]
	s_mov_b32 m0, s51
	s_nop 0
	global_load_lds_dwordx4 v[202:203], off
	s_mov_b32 m0, s52
	s_nop 0
	global_load_lds_dwordx4 v[226:227], off
	s_waitcnt vmcnt(8)
	s_waitcnt lgkmcnt(0)
	s_barrier
	s_setprio 1
	s_waitcnt lgkmcnt(0)
	v_mfma_f32_16x16x32_bf16 v[60:63], v[160:163], v[192:195], v[60:63]
	v_mfma_f32_16x16x32_bf16 v[56:59], v[168:171], v[192:195], v[56:59]
	v_mfma_f32_16x16x32_bf16 v[44:47], v[160:163], v[210:213], v[44:47]
	v_mfma_f32_16x16x32_bf16 v[40:43], v[168:171], v[210:213], v[40:43]
	v_mfma_f32_16x16x32_bf16 v[28:31], v[160:163], v[218:221], v[28:31]
	v_mfma_f32_16x16x32_bf16 v[24:27], v[168:171], v[218:221], v[24:27]
	v_mfma_f32_16x16x32_bf16 v[12:15], v[160:163], v[240:243], v[12:15]
	v_mfma_f32_16x16x32_bf16 v[8:11], v[168:171], v[240:243], v[8:11]
	v_mfma_f32_16x16x32_bf16 v[60:63], v[164:167], v[206:209], v[60:63]
	v_mfma_f32_16x16x32_bf16 v[56:59], v[172:175], v[206:209], v[56:59]
	v_mfma_f32_16x16x32_bf16 v[44:47], v[164:167], v[214:217], v[44:47]
	v_mfma_f32_16x16x32_bf16 v[40:43], v[172:175], v[214:217], v[40:43]
	v_mfma_f32_16x16x32_bf16 v[28:31], v[164:167], v[222:225], v[28:31]
	v_mfma_f32_16x16x32_bf16 v[24:27], v[172:175], v[222:225], v[24:27]
	v_mfma_f32_16x16x32_bf16 v[12:15], v[164:167], v[244:247], v[12:15]
	v_mfma_f32_16x16x32_bf16 v[8:11], v[172:175], v[244:247], v[8:11]
	v_mfma_f32_16x16x32_bf16 v[52:55], v[176:179], v[192:195], v[52:55]
	v_mfma_f32_16x16x32_bf16 v[48:51], v[184:187], v[192:195], v[48:51]
	v_mfma_f32_16x16x32_bf16 v[36:39], v[176:179], v[210:213], v[36:39]
	v_mfma_f32_16x16x32_bf16 v[32:35], v[184:187], v[210:213], v[32:35]
	v_mfma_f32_16x16x32_bf16 v[20:23], v[176:179], v[218:221], v[20:23]
	v_mfma_f32_16x16x32_bf16 v[16:19], v[184:187], v[218:221], v[16:19]
	v_mfma_f32_16x16x32_bf16 v[4:7], v[176:179], v[240:243], v[4:7]
	v_mfma_f32_16x16x32_bf16 v[0:3], v[184:187], v[240:243], v[0:3]
	v_mfma_f32_16x16x32_bf16 v[52:55], v[180:183], v[206:209], v[52:55]
	v_mfma_f32_16x16x32_bf16 v[48:51], v[188:191], v[206:209], v[48:51]
	v_mfma_f32_16x16x32_bf16 v[36:39], v[180:183], v[214:217], v[36:39]
	v_mfma_f32_16x16x32_bf16 v[32:35], v[188:191], v[214:217], v[32:35]
	v_mfma_f32_16x16x32_bf16 v[20:23], v[180:183], v[222:225], v[20:23]
	v_mfma_f32_16x16x32_bf16 v[16:19], v[188:191], v[222:225], v[16:19]
	v_mfma_f32_16x16x32_bf16 v[4:7], v[180:183], v[244:247], v[4:7]
	v_mfma_f32_16x16x32_bf16 v[0:3], v[188:191], v[244:247], v[0:3]
	s_setprio 0
	s_barrier
	s_add_i32 s73, 0, 0x18000
	s_add_i32 s74, 0, 0x1c000
	v_add_u32_e32 v172, s73, v158
	v_add_u32_e32 v188, s74, v158
	ds_read_b128 v[160:163], v172
	ds_read_b128 v[164:167], v172 offset:1024
	ds_read_b128 v[168:171], v172 offset:2048
	ds_read_b128 v[172:175], v172 offset:3072
	ds_read_b128 v[176:179], v188
	ds_read_b128 v[180:183], v188 offset:1024
	ds_read_b128 v[184:187], v188 offset:2048
	ds_read_b128 v[188:191], v188 offset:3072
	s_add_u32 s42, s42, 0x40000
	s_addc_u32 s43, s43, 0
	s_mov_b32 m0, s53
	v_lshl_add_u64 v[248:249], s[42:43], 0, v[136:137]
	ds_read_b128 v[192:195], v159 offset:32768
	ds_read_b128 v[206:209], v159 offset:33792
	ds_read_b128 v[210:213], v159 offset:34816
	ds_read_b128 v[214:217], v159 offset:35840
	ds_read_b128 v[218:221], v159 offset:36864
	ds_read_b128 v[222:225], v159 offset:37888
	ds_read_b128 v[240:243], v159 offset:38912
	ds_read_b128 v[244:247], v159 offset:39936
	global_load_lds_dwordx4 v[248:249], off
	v_lshl_add_u64 v[248:249], s[42:43], 0, v[132:133]
	s_mov_b32 m0, s54
	s_nop 0
	global_load_lds_dwordx4 v[248:249], off
	s_waitcnt vmcnt(8)
	s_waitcnt lgkmcnt(0)
	s_barrier
	s_setprio 1
	s_waitcnt lgkmcnt(0)
	v_mfma_f32_16x16x32_bf16 v[126:129], v[160:163], v[192:195], v[126:129]
	v_mfma_f32_16x16x32_bf16 v[122:125], v[168:171], v[192:195], v[122:125]
	v_mfma_f32_16x16x32_bf16 v[110:113], v[160:163], v[210:213], v[110:113]
	v_mfma_f32_16x16x32_bf16 v[106:109], v[168:171], v[210:213], v[106:109]
	v_mfma_f32_16x16x32_bf16 v[94:97], v[160:163], v[218:221], v[94:97]
	v_mfma_f32_16x16x32_bf16 v[90:93], v[168:171], v[218:221], v[90:93]
	v_mfma_f32_16x16x32_bf16 v[76:79], v[160:163], v[240:243], v[76:79]
	v_mfma_f32_16x16x32_bf16 v[72:75], v[168:171], v[240:243], v[72:75]
	v_mfma_f32_16x16x32_bf16 v[126:129], v[164:167], v[206:209], v[126:129]
	v_mfma_f32_16x16x32_bf16 v[122:125], v[172:175], v[206:209], v[122:125]
	v_mfma_f32_16x16x32_bf16 v[110:113], v[164:167], v[214:217], v[110:113]
	v_mfma_f32_16x16x32_bf16 v[106:109], v[172:175], v[214:217], v[106:109]
	v_mfma_f32_16x16x32_bf16 v[94:97], v[164:167], v[222:225], v[94:97]
	v_mfma_f32_16x16x32_bf16 v[90:93], v[172:175], v[222:225], v[90:93]
	v_mfma_f32_16x16x32_bf16 v[76:79], v[164:167], v[244:247], v[76:79]
	v_mfma_f32_16x16x32_bf16 v[72:75], v[172:175], v[244:247], v[72:75]
	v_mfma_f32_16x16x32_bf16 v[118:121], v[176:179], v[192:195], v[118:121]
	v_mfma_f32_16x16x32_bf16 v[114:117], v[184:187], v[192:195], v[114:117]
	v_mfma_f32_16x16x32_bf16 v[102:105], v[176:179], v[210:213], v[102:105]
	v_mfma_f32_16x16x32_bf16 v[98:101], v[184:187], v[210:213], v[98:101]
	v_mfma_f32_16x16x32_bf16 v[86:89], v[176:179], v[218:221], v[86:89]
	v_mfma_f32_16x16x32_bf16 v[82:85], v[184:187], v[218:221], v[82:85]
	v_mfma_f32_16x16x32_bf16 v[68:71], v[176:179], v[240:243], v[68:71]
	v_mfma_f32_16x16x32_bf16 v[64:67], v[184:187], v[240:243], v[64:67]
	v_mfma_f32_16x16x32_bf16 v[118:121], v[180:183], v[206:209], v[118:121]
	v_mfma_f32_16x16x32_bf16 v[114:117], v[188:191], v[206:209], v[114:117]
	v_mfma_f32_16x16x32_bf16 v[102:105], v[180:183], v[214:217], v[102:105]
	v_mfma_f32_16x16x32_bf16 v[98:101], v[188:191], v[214:217], v[98:101]
	v_mfma_f32_16x16x32_bf16 v[86:89], v[180:183], v[222:225], v[86:89]
	v_mfma_f32_16x16x32_bf16 v[82:85], v[188:191], v[222:225], v[82:85]
	v_mfma_f32_16x16x32_bf16 v[68:71], v[180:183], v[244:247], v[68:71]
	v_mfma_f32_16x16x32_bf16 v[64:67], v[188:191], v[244:247], v[64:67]
	s_setprio 0
	s_barrier
	s_add_i32 s42, s73, s49
	v_lshl_add_u64 v[198:199], v[198:199], 0, s[18:19]
	s_mov_b32 m0, s42
	ds_read_b128 v[192:195], v159 offset:49152
	ds_read_b128 v[206:209], v159 offset:50176
	ds_read_b128 v[210:213], v159 offset:51200
	ds_read_b128 v[214:217], v159 offset:52224
	ds_read_b128 v[218:221], v159 offset:53248
	ds_read_b128 v[222:225], v159 offset:54272
	ds_read_b128 v[240:243], v159 offset:55296
	ds_read_b128 v[244:247], v159 offset:56320
	global_load_lds_dwordx4 v[198:199], off
	s_add_i32 m0, s42, 0x2000
	s_add_u32 s40, s40, 0x40080
	v_lshl_add_u64 v[198:199], v[200:201], 0, s[18:19]
	s_addc_u32 s41, s41, 0
	s_add_i32 s42, s74, s49
	global_load_lds_dwordx4 v[198:199], off
	v_lshl_add_u64 v[198:199], s[40:41], 0, v[134:135]
	s_mov_b32 m0, s42
	s_nop 0
	global_load_lds_dwordx4 v[198:199], off
	v_lshl_add_u64 v[198:199], s[40:41], 0, v[130:131]
	s_add_i32 m0, s42, 0x2000
	s_nop 0
	global_load_lds_dwordx4 v[198:199], off
	v_lshl_add_u64 v[198:199], v[202:203], 0, s[18:19]
	s_mov_b32 m0, s57
	s_nop 0
	global_load_lds_dwordx4 v[198:199], off
	v_lshl_add_u64 v[198:199], v[226:227], 0, s[18:19]
	s_mov_b32 m0, s62
	s_nop 0
	global_load_lds_dwordx4 v[198:199], off
	s_waitcnt vmcnt(8)
	s_waitcnt lgkmcnt(0)
	s_barrier
	s_setprio 1
	s_waitcnt lgkmcnt(0)
	v_mfma_f32_16x16x32_bf16 v[60:63], v[160:163], v[192:195], v[60:63]
	v_mfma_f32_16x16x32_bf16 v[56:59], v[168:171], v[192:195], v[56:59]
	v_mfma_f32_16x16x32_bf16 v[44:47], v[160:163], v[210:213], v[44:47]
	v_mfma_f32_16x16x32_bf16 v[40:43], v[168:171], v[210:213], v[40:43]
	v_mfma_f32_16x16x32_bf16 v[28:31], v[160:163], v[218:221], v[28:31]
	v_mfma_f32_16x16x32_bf16 v[24:27], v[168:171], v[218:221], v[24:27]
	v_mfma_f32_16x16x32_bf16 v[12:15], v[160:163], v[240:243], v[12:15]
	v_mfma_f32_16x16x32_bf16 v[8:11], v[168:171], v[240:243], v[8:11]
	v_mfma_f32_16x16x32_bf16 v[60:63], v[164:167], v[206:209], v[60:63]
	v_mfma_f32_16x16x32_bf16 v[56:59], v[172:175], v[206:209], v[56:59]
	v_mfma_f32_16x16x32_bf16 v[44:47], v[164:167], v[214:217], v[44:47]
	v_mfma_f32_16x16x32_bf16 v[40:43], v[172:175], v[214:217], v[40:43]
	v_mfma_f32_16x16x32_bf16 v[28:31], v[164:167], v[222:225], v[28:31]
	v_mfma_f32_16x16x32_bf16 v[24:27], v[172:175], v[222:225], v[24:27]
	v_mfma_f32_16x16x32_bf16 v[12:15], v[164:167], v[244:247], v[12:15]
	v_mfma_f32_16x16x32_bf16 v[8:11], v[172:175], v[244:247], v[8:11]
	v_mfma_f32_16x16x32_bf16 v[52:55], v[176:179], v[192:195], v[52:55]
	v_mfma_f32_16x16x32_bf16 v[48:51], v[184:187], v[192:195], v[48:51]
	v_mfma_f32_16x16x32_bf16 v[36:39], v[176:179], v[210:213], v[36:39]
	v_mfma_f32_16x16x32_bf16 v[32:35], v[184:187], v[210:213], v[32:35]
	v_mfma_f32_16x16x32_bf16 v[20:23], v[176:179], v[218:221], v[20:23]
	v_mfma_f32_16x16x32_bf16 v[16:19], v[184:187], v[218:221], v[16:19]
	v_mfma_f32_16x16x32_bf16 v[4:7], v[176:179], v[240:243], v[4:7]
	v_mfma_f32_16x16x32_bf16 v[0:3], v[184:187], v[240:243], v[0:3]
	v_mfma_f32_16x16x32_bf16 v[52:55], v[180:183], v[206:209], v[52:55]
	v_mfma_f32_16x16x32_bf16 v[48:51], v[188:191], v[206:209], v[48:51]
	v_mfma_f32_16x16x32_bf16 v[36:39], v[180:183], v[214:217], v[36:39]
	v_mfma_f32_16x16x32_bf16 v[32:35], v[188:191], v[214:217], v[32:35]
	v_mfma_f32_16x16x32_bf16 v[20:23], v[180:183], v[222:225], v[20:23]
	v_mfma_f32_16x16x32_bf16 v[16:19], v[188:191], v[222:225], v[16:19]
	v_mfma_f32_16x16x32_bf16 v[4:7], v[180:183], v[244:247], v[4:7]
	v_mfma_f32_16x16x32_bf16 v[0:3], v[188:191], v[244:247], v[0:3]
	s_setprio 0
	s_barrier
	s_add_i32 s72, s72, 2
	s_add_u32 s68, s68, 0x100
	s_addc_u32 s69, s69, 0
	s_add_u32 s38, s38, 0x100
	s_addc_u32 s39, s39, 0
	s_cmp_gt_u32 s72, 13
	s_cbranch_scc0 .LBB0_651
	s_and_b64 vcc, exec, s[4:5]
	s_cbranch_vccz .LBB0_654
	s_barrier
